# attention loop: 9 LDS read buffers, prefetch distance 8, 18-step unroll, on top of v22
# baseline (speedup 1.0000x reference)
.Lattn_fx_loop:
	ds_read_b128 v[188:191], v187 offset:22528
	ds_read_b128 v[168:171], v187 offset:22560
	ds_read_b128 v[218:221], v187 offset:22592
	ds_read_b128 v[222:225], v187 offset:22624
	s_waitcnt lgkmcnt(7)
	v_mfma_f32_32x32x16_bf16 v[16:31], v[128:131], v[112:115], v[16:31]
	ds_read_b128 v[226:229], v187 offset:22656
	s_waitcnt vmcnt(0)
	ds_write_b128 v211, v[176:179] offset:45056
	s_and_saveexec_b64 s[42:43], s[36:37]
	s_cbranch_execz .Lattn_fx_w0
	ds_write_b128 v186, v[172:175] offset:45056
.Lattn_fx_w0:
	s_or_b64 exec, exec, s[42:43]
	ds_write_b128 v208, v[180:183] offset:58368
	v_exp_f32_e32 v48, v48
	v_exp_f32_e32 v49, v49
	v_exp_f32_e32 v50, v50
	s_waitcnt lgkmcnt(9)
	v_mfma_f32_32x32x16_bf16 v[32:47], v[132:135], v[112:115], v[32:47]
	ds_read_b128 v[128:131], v187 offset:22688
	global_load_dwordx4 v[176:179], v212, s[6:7]
	s_and_saveexec_b64 s[42:43], s[36:37]
	s_cbranch_execz .Lattn_fx_g1
	global_load_dwordx4 v[172:175], v214, s[6:7]
.Lattn_fx_g1:
	s_or_b64 exec, exec, s[42:43]
	global_load_dwordx4 v[180:183], v204, s[40:41]
	s_add_u32 s6, s6, 0x18000
	s_addc_u32 s7, s7, 0
	s_add_u32 s40, s40, 0x80
	s_addc_u32 s41, s41, 0
	v_exp_f32_e32 v51, v51
	v_exp_f32_e32 v52, v52
	v_exp_f32_e32 v53, v53
	s_waitcnt lgkmcnt(9)
	v_mfma_f32_32x32x16_bf16 v[16:31], v[136:139], v[116:119], v[16:31]
	ds_read_b128 v[132:135], v209 offset:13376
	v_exp_f32_e32 v54, v54
	v_exp_f32_e32 v55, v55
	v_cvt_pk_bf16_f32 v120, v48, v49
	v_cvt_pk_bf16_f32 v121, v50, v51
	s_waitcnt lgkmcnt(9)
	v_mfma_f32_32x32x16_bf16 v[32:47], v[140:143], v[116:119], v[32:47]
	ds_read_b128 v[136:139], v209 offset:17984
	v_cvt_pk_bf16_f32 v122, v52, v53
	v_cvt_pk_bf16_f32 v123, v54, v55
	v_exp_f32_e32 v56, v56
	v_exp_f32_e32 v57, v57
	s_waitcnt lgkmcnt(9)
	v_mfma_f32_32x32x16_bf16 v[96:111], v[188:191], v[164:167], v[0:15]
	ds_read_b128 v[140:143], v187 offset:29184
	v_exp_f32_e32 v58, v58
	v_exp_f32_e32 v59, v59
	v_add_f32_e32 v48, v64, v48
	v_add_f32_e32 v244, v244, v48
	s_waitcnt lgkmcnt(9)
	v_mfma_f32_32x32x16_bf16 v[96:111], v[168:171], v[144:147], v[96:111]
	ds_read_b128 v[188:191], v187 offset:29216
	v_exp_f32_e32 v60, v60
	v_exp_f32_e32 v61, v61
	v_add_f32_e32 v49, v65, v49
	v_add_f32_e32 v245, v245, v49
	s_waitcnt lgkmcnt(9)
	v_mfma_f32_32x32x16_bf16 v[96:111], v[218:221], v[148:151], v[96:111]
	ds_read_b128 v[168:171], v187 offset:29248
	v_exp_f32_e32 v62, v62
	v_exp_f32_e32 v63, v63
	v_add_f32_e32 v50, v66, v50
	v_add_f32_e32 v242, v242, v50
	s_waitcnt lgkmcnt(9)
	v_mfma_f32_32x32x16_bf16 v[96:111], v[222:225], v[152:155], v[96:111]
	ds_read_b128 v[218:221], v209 offset:13408
	v_cvt_pk_bf16_f32 v124, v56, v57
	v_cvt_pk_bf16_f32 v125, v58, v59
	v_cvt_pk_bf16_f32 v126, v60, v61
	v_cvt_pk_bf16_f32 v127, v62, v63
	v_add_f32_e32 v51, v67, v51
	v_add_f32_e32 v243, v243, v51
	s_waitcnt lgkmcnt(9)
	v_mfma_f32_32x32x16_bf16 v[96:111], v[226:229], v[156:159], v[96:111]
	ds_read_b128 v[222:225], v209 offset:18016
	v_add_f32_e32 v52, v68, v52
	v_add_f32_e32 v240, v240, v52
	v_add_f32_e32 v53, v69, v53
	v_add_f32_e32 v241, v241, v53
	v_add_f32_e32 v54, v70, v54
	v_add_f32_e32 v238, v238, v54
	s_waitcnt lgkmcnt(7)
	v_mfma_f32_32x32x16_bf16 v[96:111], v[128:131], v[160:163], v[96:111]
	ds_read_b128 v[226:229], v187 offset:29280
	v_add_f32_e32 v55, v71, v55
	v_add_f32_e32 v239, v239, v55
	v_add_f32_e32 v56, v72, v56
	v_add_f32_e32 v236, v236, v56
	v_add_f32_e32 v57, v73, v57
	v_add_f32_e32 v237, v237, v57
	s_waitcnt lgkmcnt(7)
	v_mfma_f32_32x32x16_bf16 v[16:31], v[132:135], v[120:123], v[16:31]
	ds_read_b128 v[128:131], v187 offset:29312
	v_add_f32_e32 v58, v74, v58
	v_add_f32_e32 v234, v234, v58
	v_add_f32_e32 v59, v75, v59
	v_add_f32_e32 v235, v235, v59
	v_add_f32_e32 v60, v76, v60
	v_add_f32_e32 v232, v232, v60
	s_waitcnt lgkmcnt(7)
	v_mfma_f32_32x32x16_bf16 v[32:47], v[136:139], v[120:123], v[32:47]
	ds_read_b128 v[132:135], v187 offset:29344
	v_add_f32_e32 v61, v77, v61
	v_add_f32_e32 v233, v233, v61
	v_add_f32_e32 v62, v78, v62
	v_add_f32_e32 v230, v230, v62
	s_waitcnt lgkmcnt(7)
	v_mfma_f32_32x32x16_bf16 v[80:95], v[140:143], v[164:167], v[0:15]
	ds_read_b128 v[136:139], v209 offset:35840
	v_exp_f32_e32 v96, v96
	v_exp_f32_e32 v97, v97
	v_exp_f32_e32 v98, v98
	s_waitcnt lgkmcnt(7)
	v_mfma_f32_32x32x16_bf16 v[80:95], v[188:191], v[144:147], v[80:95]
	ds_read_b128 v[140:143], v209 offset:40448
	v_exp_f32_e32 v99, v99
	v_exp_f32_e32 v100, v100
	v_exp_f32_e32 v101, v101
	s_waitcnt lgkmcnt(7)
	v_mfma_f32_32x32x16_bf16 v[80:95], v[168:171], v[148:151], v[80:95]
	ds_read_b128 v[188:191], v209 offset:35872
	v_exp_f32_e32 v102, v102
	v_exp_f32_e32 v103, v103
	v_cvt_pk_bf16_f32 v112, v96, v97
	v_cvt_pk_bf16_f32 v113, v98, v99
	s_waitcnt lgkmcnt(7)
	v_mfma_f32_32x32x16_bf16 v[16:31], v[218:221], v[124:127], v[16:31]
	ds_read_b128 v[168:171], v209 offset:40480
	v_cvt_pk_bf16_f32 v114, v100, v101
	v_cvt_pk_bf16_f32 v115, v102, v103
	v_exp_f32_e32 v104, v104
	v_exp_f32_e32 v105, v105
	s_waitcnt lgkmcnt(7)
	v_mfma_f32_32x32x16_bf16 v[32:47], v[222:225], v[124:127], v[32:47]
	v_exp_f32_e32 v106, v106
	v_exp_f32_e32 v107, v107
	v_exp_f32_e32 v108, v108
	s_waitcnt lgkmcnt(6)
	v_mfma_f32_32x32x16_bf16 v[80:95], v[226:229], v[152:155], v[80:95]
	v_exp_f32_e32 v109, v109
	v_exp_f32_e32 v110, v110
	v_exp_f32_e32 v111, v111
	s_waitcnt lgkmcnt(5)
	v_mfma_f32_32x32x16_bf16 v[80:95], v[128:131], v[156:159], v[80:95]
	v_cvt_pk_bf16_f32 v116, v104, v105
	v_cvt_pk_bf16_f32 v117, v106, v107
	v_cvt_pk_bf16_f32 v118, v108, v109
	v_cvt_pk_bf16_f32 v119, v110, v111
	s_waitcnt lgkmcnt(4)
	v_mfma_f32_32x32x16_bf16 v[80:95], v[132:135], v[160:163], v[80:95]
	v_add_f32_e32 v63, v79, v63
	v_add_f32_e32 v231, v231, v63
	s_waitcnt lgkmcnt(4)
	s_barrier
	ds_read_b128 v[218:221], v187 offset:45056
	ds_read_b128 v[222:225], v187 offset:45088
	ds_read_b128 v[226:229], v187 offset:45120
	ds_read_b128 v[128:131], v187 offset:45152
	s_waitcnt lgkmcnt(7)
	v_mfma_f32_32x32x16_bf16 v[16:31], v[136:139], v[112:115], v[16:31]
	ds_read_b128 v[132:135], v187 offset:45184
	s_waitcnt vmcnt(0)
	ds_write_b128 v211, v[176:179] offset:0
	s_and_saveexec_b64 s[42:43], s[36:37]
	s_cbranch_execz .Lattn_fx_w2
	ds_write_b128 v186, v[172:175] offset:0
.Lattn_fx_w2:
	s_or_b64 exec, exec, s[42:43]
	ds_write_b128 v208, v[180:183] offset:13312
	v_exp_f32_e32 v80, v80
	v_exp_f32_e32 v81, v81
	v_exp_f32_e32 v82, v82
	s_waitcnt lgkmcnt(9)
	v_mfma_f32_32x32x16_bf16 v[32:47], v[140:143], v[112:115], v[32:47]
	ds_read_b128 v[136:139], v187 offset:45216
	global_load_dwordx4 v[176:179], v212, s[6:7]
	s_and_saveexec_b64 s[42:43], s[36:37]
	s_cbranch_execz .Lattn_fx_g3
	global_load_dwordx4 v[172:175], v214, s[6:7]
.Lattn_fx_g3:
	s_or_b64 exec, exec, s[42:43]
	global_load_dwordx4 v[180:183], v204, s[40:41]
	s_add_u32 s6, s6, 0x18000
	s_addc_u32 s7, s7, 0
	s_add_u32 s40, s40, 0x80
	s_addc_u32 s41, s41, 0
	v_exp_f32_e32 v83, v83
	v_exp_f32_e32 v84, v84
	v_exp_f32_e32 v85, v85
	s_waitcnt lgkmcnt(9)
	v_mfma_f32_32x32x16_bf16 v[16:31], v[188:191], v[116:119], v[16:31]
	ds_read_b128 v[140:143], v209 offset:35904
	v_exp_f32_e32 v86, v86
	v_exp_f32_e32 v87, v87
	v_cvt_pk_bf16_f32 v120, v80, v81
	v_cvt_pk_bf16_f32 v121, v82, v83
	s_waitcnt lgkmcnt(9)
	v_mfma_f32_32x32x16_bf16 v[32:47], v[168:171], v[116:119], v[32:47]
	ds_read_b128 v[188:191], v209 offset:40512
	v_cvt_pk_bf16_f32 v122, v84, v85
	v_cvt_pk_bf16_f32 v123, v86, v87
	v_exp_f32_e32 v88, v88
	v_exp_f32_e32 v89, v89
	s_waitcnt lgkmcnt(9)
	v_mfma_f32_32x32x16_bf16 v[64:79], v[218:221], v[164:167], v[0:15]
	ds_read_b128 v[168:171], v187 offset:51712
	v_exp_f32_e32 v90, v90
	v_exp_f32_e32 v91, v91
	v_add_f32_e32 v80, v96, v80
	v_add_f32_e32 v244, v244, v80
	s_waitcnt lgkmcnt(9)
	v_mfma_f32_32x32x16_bf16 v[64:79], v[222:225], v[144:147], v[64:79]
	ds_read_b128 v[218:221], v187 offset:51744
	v_exp_f32_e32 v92, v92
	v_exp_f32_e32 v93, v93
	v_add_f32_e32 v81, v97, v81
	v_add_f32_e32 v245, v245, v81
	s_waitcnt lgkmcnt(9)
	v_mfma_f32_32x32x16_bf16 v[64:79], v[226:229], v[148:151], v[64:79]
	ds_read_b128 v[222:225], v187 offset:51776
	v_exp_f32_e32 v94, v94
	v_exp_f32_e32 v95, v95
	v_add_f32_e32 v82, v98, v82
	v_add_f32_e32 v242, v242, v82
	s_waitcnt lgkmcnt(9)
	v_mfma_f32_32x32x16_bf16 v[64:79], v[128:131], v[152:155], v[64:79]
	ds_read_b128 v[226:229], v209 offset:35936
	v_cvt_pk_bf16_f32 v124, v88, v89
	v_cvt_pk_bf16_f32 v125, v90, v91
	v_cvt_pk_bf16_f32 v126, v92, v93
	v_cvt_pk_bf16_f32 v127, v94, v95
	v_add_f32_e32 v83, v99, v83
	v_add_f32_e32 v243, v243, v83
	s_waitcnt lgkmcnt(9)
	v_mfma_f32_32x32x16_bf16 v[64:79], v[132:135], v[156:159], v[64:79]
	ds_read_b128 v[128:131], v209 offset:40544
	v_add_f32_e32 v84, v100, v84
	v_add_f32_e32 v240, v240, v84
	v_add_f32_e32 v85, v101, v85
	v_add_f32_e32 v241, v241, v85
	v_add_f32_e32 v86, v102, v86
	v_add_f32_e32 v238, v238, v86
	s_waitcnt lgkmcnt(7)
	v_mfma_f32_32x32x16_bf16 v[64:79], v[136:139], v[160:163], v[64:79]
	ds_read_b128 v[132:135], v187 offset:51808
	v_add_f32_e32 v87, v103, v87
	v_add_f32_e32 v239, v239, v87
	v_add_f32_e32 v88, v104, v88
	v_add_f32_e32 v236, v236, v88
	v_add_f32_e32 v89, v105, v89
	v_add_f32_e32 v237, v237, v89
	s_waitcnt lgkmcnt(7)
	v_mfma_f32_32x32x16_bf16 v[16:31], v[140:143], v[120:123], v[16:31]
	ds_read_b128 v[136:139], v187 offset:51840
	v_add_f32_e32 v90, v106, v90
	v_add_f32_e32 v234, v234, v90
	v_add_f32_e32 v91, v107, v91
	v_add_f32_e32 v235, v235, v91
	v_add_f32_e32 v92, v108, v92
	v_add_f32_e32 v232, v232, v92
	s_waitcnt lgkmcnt(7)
	v_mfma_f32_32x32x16_bf16 v[32:47], v[188:191], v[120:123], v[32:47]
	ds_read_b128 v[140:143], v187 offset:51872
	v_add_f32_e32 v93, v109, v93
	v_add_f32_e32 v233, v233, v93
	v_add_f32_e32 v94, v110, v94
	v_add_f32_e32 v230, v230, v94
	s_waitcnt lgkmcnt(7)
	v_mfma_f32_32x32x16_bf16 v[48:63], v[168:171], v[164:167], v[0:15]
	ds_read_b128 v[188:191], v209 offset:58368
	v_exp_f32_e32 v64, v64
	v_exp_f32_e32 v65, v65
	v_exp_f32_e32 v66, v66
	s_waitcnt lgkmcnt(7)
	v_mfma_f32_32x32x16_bf16 v[48:63], v[218:221], v[144:147], v[48:63]
	ds_read_b128 v[168:171], v209 offset:62976
	v_exp_f32_e32 v67, v67
	v_exp_f32_e32 v68, v68
	v_exp_f32_e32 v69, v69
	s_waitcnt lgkmcnt(7)
	v_mfma_f32_32x32x16_bf16 v[48:63], v[222:225], v[148:151], v[48:63]
	ds_read_b128 v[218:221], v209 offset:58400
	v_exp_f32_e32 v70, v70
	v_exp_f32_e32 v71, v71
	v_cvt_pk_bf16_f32 v112, v64, v65
	v_cvt_pk_bf16_f32 v113, v66, v67
	s_waitcnt lgkmcnt(7)
	v_mfma_f32_32x32x16_bf16 v[16:31], v[226:229], v[124:127], v[16:31]
	ds_read_b128 v[222:225], v209 offset:63008
	v_cvt_pk_bf16_f32 v114, v68, v69
	v_cvt_pk_bf16_f32 v115, v70, v71
	v_exp_f32_e32 v72, v72
	v_exp_f32_e32 v73, v73
	s_waitcnt lgkmcnt(7)
	v_mfma_f32_32x32x16_bf16 v[32:47], v[128:131], v[124:127], v[32:47]
	v_exp_f32_e32 v74, v74
	v_exp_f32_e32 v75, v75
	v_exp_f32_e32 v76, v76
	s_waitcnt lgkmcnt(6)
	v_mfma_f32_32x32x16_bf16 v[48:63], v[132:135], v[152:155], v[48:63]
	v_exp_f32_e32 v77, v77
	v_exp_f32_e32 v78, v78
	v_exp_f32_e32 v79, v79
	s_waitcnt lgkmcnt(5)
	v_mfma_f32_32x32x16_bf16 v[48:63], v[136:139], v[156:159], v[48:63]
	v_cvt_pk_bf16_f32 v116, v72, v73
	v_cvt_pk_bf16_f32 v117, v74, v75
	v_cvt_pk_bf16_f32 v118, v76, v77
	v_cvt_pk_bf16_f32 v119, v78, v79
	s_waitcnt lgkmcnt(4)
	v_mfma_f32_32x32x16_bf16 v[48:63], v[140:143], v[160:163], v[48:63]
	v_add_f32_e32 v95, v111, v95
	v_add_f32_e32 v231, v231, v95
	s_waitcnt lgkmcnt(4)
	s_barrier
	ds_read_b128 v[226:229], v187 offset:0
	ds_read_b128 v[128:131], v187 offset:32
	ds_read_b128 v[132:135], v187 offset:64
	ds_read_b128 v[136:139], v187 offset:96
	s_waitcnt lgkmcnt(7)
	v_mfma_f32_32x32x16_bf16 v[16:31], v[188:191], v[112:115], v[16:31]
	ds_read_b128 v[140:143], v187 offset:128
	s_waitcnt vmcnt(0)
	ds_write_b128 v211, v[176:179] offset:22528
	s_and_saveexec_b64 s[42:43], s[36:37]
	s_cbranch_execz .Lattn_fx_w4
	ds_write_b128 v186, v[172:175] offset:22528
.Lattn_fx_w4:
	s_or_b64 exec, exec, s[42:43]
	ds_write_b128 v208, v[180:183] offset:35840
	v_exp_f32_e32 v48, v48
	v_exp_f32_e32 v49, v49
	v_exp_f32_e32 v50, v50
	s_waitcnt lgkmcnt(9)
	v_mfma_f32_32x32x16_bf16 v[32:47], v[168:171], v[112:115], v[32:47]
	ds_read_b128 v[188:191], v187 offset:160
	global_load_dwordx4 v[176:179], v212, s[6:7]
	s_and_saveexec_b64 s[42:43], s[36:37]
	s_cbranch_execz .Lattn_fx_g5
	global_load_dwordx4 v[172:175], v214, s[6:7]
.Lattn_fx_g5:
	s_or_b64 exec, exec, s[42:43]
	global_load_dwordx4 v[180:183], v204, s[40:41]
	s_add_u32 s6, s6, 0x18000
	s_addc_u32 s7, s7, 0
	s_add_u32 s40, s40, 0x80
	s_addc_u32 s41, s41, 0
	v_exp_f32_e32 v51, v51
	v_exp_f32_e32 v52, v52
	v_exp_f32_e32 v53, v53
	s_waitcnt lgkmcnt(9)
	v_mfma_f32_32x32x16_bf16 v[16:31], v[218:221], v[116:119], v[16:31]
	ds_read_b128 v[168:171], v209 offset:58432
	v_exp_f32_e32 v54, v54
	v_exp_f32_e32 v55, v55
	v_cvt_pk_bf16_f32 v120, v48, v49
	v_cvt_pk_bf16_f32 v121, v50, v51
	s_waitcnt lgkmcnt(9)
	v_mfma_f32_32x32x16_bf16 v[32:47], v[222:225], v[116:119], v[32:47]
	ds_read_b128 v[218:221], v209 offset:63040
	v_cvt_pk_bf16_f32 v122, v52, v53
	v_cvt_pk_bf16_f32 v123, v54, v55
	v_exp_f32_e32 v56, v56
	v_exp_f32_e32 v57, v57
	s_waitcnt lgkmcnt(9)
	v_mfma_f32_32x32x16_bf16 v[96:111], v[226:229], v[164:167], v[0:15]
	ds_read_b128 v[222:225], v187 offset:6656
	v_exp_f32_e32 v58, v58
	v_exp_f32_e32 v59, v59
	v_add_f32_e32 v48, v64, v48
	v_add_f32_e32 v244, v244, v48
	s_waitcnt lgkmcnt(9)
	v_mfma_f32_32x32x16_bf16 v[96:111], v[128:131], v[144:147], v[96:111]
	ds_read_b128 v[226:229], v187 offset:6688
	v_exp_f32_e32 v60, v60
	v_exp_f32_e32 v61, v61
	v_add_f32_e32 v49, v65, v49
	v_add_f32_e32 v245, v245, v49
	s_waitcnt lgkmcnt(9)
	v_mfma_f32_32x32x16_bf16 v[96:111], v[132:135], v[148:151], v[96:111]
	ds_read_b128 v[128:131], v187 offset:6720
	v_exp_f32_e32 v62, v62
	v_exp_f32_e32 v63, v63
	v_add_f32_e32 v50, v66, v50
	v_add_f32_e32 v242, v242, v50
	s_waitcnt lgkmcnt(9)
	v_mfma_f32_32x32x16_bf16 v[96:111], v[136:139], v[152:155], v[96:111]
	ds_read_b128 v[132:135], v209 offset:58464
	v_cvt_pk_bf16_f32 v124, v56, v57
	v_cvt_pk_bf16_f32 v125, v58, v59
	v_cvt_pk_bf16_f32 v126, v60, v61
	v_cvt_pk_bf16_f32 v127, v62, v63
	v_add_f32_e32 v51, v67, v51
	v_add_f32_e32 v243, v243, v51
	s_waitcnt lgkmcnt(9)
	v_mfma_f32_32x32x16_bf16 v[96:111], v[140:143], v[156:159], v[96:111]
	ds_read_b128 v[136:139], v209 offset:63072
	v_add_f32_e32 v52, v68, v52
	v_add_f32_e32 v240, v240, v52
	v_add_f32_e32 v53, v69, v53
	v_add_f32_e32 v241, v241, v53
	v_add_f32_e32 v54, v70, v54
	v_add_f32_e32 v238, v238, v54
	s_waitcnt lgkmcnt(7)
	v_mfma_f32_32x32x16_bf16 v[96:111], v[188:191], v[160:163], v[96:111]
	ds_read_b128 v[140:143], v187 offset:6752
	v_add_f32_e32 v55, v71, v55
	v_add_f32_e32 v239, v239, v55
	v_add_f32_e32 v56, v72, v56
	v_add_f32_e32 v236, v236, v56
	v_add_f32_e32 v57, v73, v57
	v_add_f32_e32 v237, v237, v57
	s_waitcnt lgkmcnt(7)
	v_mfma_f32_32x32x16_bf16 v[16:31], v[168:171], v[120:123], v[16:31]
	ds_read_b128 v[188:191], v187 offset:6784
	v_add_f32_e32 v58, v74, v58
	v_add_f32_e32 v234, v234, v58
	v_add_f32_e32 v59, v75, v59
	v_add_f32_e32 v235, v235, v59
	v_add_f32_e32 v60, v76, v60
	v_add_f32_e32 v232, v232, v60
	s_waitcnt lgkmcnt(7)
	v_mfma_f32_32x32x16_bf16 v[32:47], v[218:221], v[120:123], v[32:47]
	ds_read_b128 v[168:171], v187 offset:6816
	v_add_f32_e32 v61, v77, v61
	v_add_f32_e32 v233, v233, v61
	v_add_f32_e32 v62, v78, v62
	v_add_f32_e32 v230, v230, v62
	s_waitcnt lgkmcnt(7)
	v_mfma_f32_32x32x16_bf16 v[80:95], v[222:225], v[164:167], v[0:15]
	ds_read_b128 v[218:221], v209 offset:13312
	v_exp_f32_e32 v96, v96
	v_exp_f32_e32 v97, v97
	v_exp_f32_e32 v98, v98
	s_waitcnt lgkmcnt(7)
	v_mfma_f32_32x32x16_bf16 v[80:95], v[226:229], v[144:147], v[80:95]
	ds_read_b128 v[222:225], v209 offset:17920
	v_exp_f32_e32 v99, v99
	v_exp_f32_e32 v100, v100
	v_exp_f32_e32 v101, v101
	s_waitcnt lgkmcnt(7)
	v_mfma_f32_32x32x16_bf16 v[80:95], v[128:131], v[148:151], v[80:95]
	ds_read_b128 v[226:229], v209 offset:13344
	v_exp_f32_e32 v102, v102
	v_exp_f32_e32 v103, v103
	v_cvt_pk_bf16_f32 v112, v96, v97
	v_cvt_pk_bf16_f32 v113, v98, v99
	s_waitcnt lgkmcnt(7)
	v_mfma_f32_32x32x16_bf16 v[16:31], v[132:135], v[124:127], v[16:31]
	ds_read_b128 v[128:131], v209 offset:17952
	v_cvt_pk_bf16_f32 v114, v100, v101
	v_cvt_pk_bf16_f32 v115, v102, v103
	v_exp_f32_e32 v104, v104
	v_exp_f32_e32 v105, v105
	s_waitcnt lgkmcnt(7)
	v_mfma_f32_32x32x16_bf16 v[32:47], v[136:139], v[124:127], v[32:47]
	v_exp_f32_e32 v106, v106
	v_exp_f32_e32 v107, v107
	v_exp_f32_e32 v108, v108
	s_waitcnt lgkmcnt(6)
	v_mfma_f32_32x32x16_bf16 v[80:95], v[140:143], v[152:155], v[80:95]
	v_exp_f32_e32 v109, v109
	v_exp_f32_e32 v110, v110
	v_exp_f32_e32 v111, v111
	s_waitcnt lgkmcnt(5)
	v_mfma_f32_32x32x16_bf16 v[80:95], v[188:191], v[156:159], v[80:95]
	v_cvt_pk_bf16_f32 v116, v104, v105
	v_cvt_pk_bf16_f32 v117, v106, v107
	v_cvt_pk_bf16_f32 v118, v108, v109
	v_cvt_pk_bf16_f32 v119, v110, v111
	s_waitcnt lgkmcnt(4)
	v_mfma_f32_32x32x16_bf16 v[80:95], v[168:171], v[160:163], v[80:95]
	v_add_f32_e32 v63, v79, v63
	v_add_f32_e32 v231, v231, v63
	s_waitcnt lgkmcnt(4)
	s_barrier
	ds_read_b128 v[132:135], v187 offset:22528
	ds_read_b128 v[136:139], v187 offset:22560
	ds_read_b128 v[140:143], v187 offset:22592
	ds_read_b128 v[188:191], v187 offset:22624
	s_waitcnt lgkmcnt(7)
	v_mfma_f32_32x32x16_bf16 v[16:31], v[218:221], v[112:115], v[16:31]
	ds_read_b128 v[168:171], v187 offset:22656
	s_waitcnt vmcnt(0)
	ds_write_b128 v211, v[176:179] offset:45056
	s_and_saveexec_b64 s[42:43], s[36:37]
	s_cbranch_execz .Lattn_fx_w6
	ds_write_b128 v186, v[172:175] offset:45056
.Lattn_fx_w6:
	s_or_b64 exec, exec, s[42:43]
	ds_write_b128 v208, v[180:183] offset:58368
	v_exp_f32_e32 v80, v80
	v_exp_f32_e32 v81, v81
	v_exp_f32_e32 v82, v82
	s_waitcnt lgkmcnt(9)
	v_mfma_f32_32x32x16_bf16 v[32:47], v[222:225], v[112:115], v[32:47]
	ds_read_b128 v[218:221], v187 offset:22688
	global_load_dwordx4 v[176:179], v212, s[6:7]
	s_and_saveexec_b64 s[42:43], s[36:37]
	s_cbranch_execz .Lattn_fx_g7
	global_load_dwordx4 v[172:175], v214, s[6:7]
.Lattn_fx_g7:
	s_or_b64 exec, exec, s[42:43]
	global_load_dwordx4 v[180:183], v204, s[40:41]
	s_add_u32 s6, s6, 0x18000
	s_addc_u32 s7, s7, 0
	s_add_u32 s40, s40, 0x80
	s_addc_u32 s41, s41, 0
	v_exp_f32_e32 v83, v83
	v_exp_f32_e32 v84, v84
	v_exp_f32_e32 v85, v85
	s_waitcnt lgkmcnt(9)
	v_mfma_f32_32x32x16_bf16 v[16:31], v[226:229], v[116:119], v[16:31]
	ds_read_b128 v[222:225], v209 offset:13376
	v_exp_f32_e32 v86, v86
	v_exp_f32_e32 v87, v87
	v_cvt_pk_bf16_f32 v120, v80, v81
	v_cvt_pk_bf16_f32 v121, v82, v83
	s_waitcnt lgkmcnt(9)
	v_mfma_f32_32x32x16_bf16 v[32:47], v[128:131], v[116:119], v[32:47]
	ds_read_b128 v[226:229], v209 offset:17984
	v_cvt_pk_bf16_f32 v122, v84, v85
	v_cvt_pk_bf16_f32 v123, v86, v87
	v_exp_f32_e32 v88, v88
	v_exp_f32_e32 v89, v89
	s_waitcnt lgkmcnt(9)
	v_mfma_f32_32x32x16_bf16 v[64:79], v[132:135], v[164:167], v[0:15]
	ds_read_b128 v[128:131], v187 offset:29184
	v_exp_f32_e32 v90, v90
	v_exp_f32_e32 v91, v91
	v_add_f32_e32 v80, v96, v80
	v_add_f32_e32 v244, v244, v80
	s_waitcnt lgkmcnt(9)
	v_mfma_f32_32x32x16_bf16 v[64:79], v[136:139], v[144:147], v[64:79]
	ds_read_b128 v[132:135], v187 offset:29216
	v_exp_f32_e32 v92, v92
	v_exp_f32_e32 v93, v93
	v_add_f32_e32 v81, v97, v81
	v_add_f32_e32 v245, v245, v81
	s_waitcnt lgkmcnt(9)
	v_mfma_f32_32x32x16_bf16 v[64:79], v[140:143], v[148:151], v[64:79]
	ds_read_b128 v[136:139], v187 offset:29248
	v_exp_f32_e32 v94, v94
	v_exp_f32_e32 v95, v95
	v_add_f32_e32 v82, v98, v82
	v_add_f32_e32 v242, v242, v82
	s_waitcnt lgkmcnt(9)
	v_mfma_f32_32x32x16_bf16 v[64:79], v[188:191], v[152:155], v[64:79]
	ds_read_b128 v[140:143], v209 offset:13408
	v_cvt_pk_bf16_f32 v124, v88, v89
	v_cvt_pk_bf16_f32 v125, v90, v91
	v_cvt_pk_bf16_f32 v126, v92, v93
	v_cvt_pk_bf16_f32 v127, v94, v95
	v_add_f32_e32 v83, v99, v83
	v_add_f32_e32 v243, v243, v83
	s_waitcnt lgkmcnt(9)
	v_mfma_f32_32x32x16_bf16 v[64:79], v[168:171], v[156:159], v[64:79]
	ds_read_b128 v[188:191], v209 offset:18016
	v_add_f32_e32 v84, v100, v84
	v_add_f32_e32 v240, v240, v84
	v_add_f32_e32 v85, v101, v85
	v_add_f32_e32 v241, v241, v85
	v_add_f32_e32 v86, v102, v86
	v_add_f32_e32 v238, v238, v86
	s_waitcnt lgkmcnt(7)
	v_mfma_f32_32x32x16_bf16 v[64:79], v[218:221], v[160:163], v[64:79]
	ds_read_b128 v[168:171], v187 offset:29280
	v_add_f32_e32 v87, v103, v87
	v_add_f32_e32 v239, v239, v87
	v_add_f32_e32 v88, v104, v88
	v_add_f32_e32 v236, v236, v88
	v_add_f32_e32 v89, v105, v89
	v_add_f32_e32 v237, v237, v89
	s_waitcnt lgkmcnt(7)
	v_mfma_f32_32x32x16_bf16 v[16:31], v[222:225], v[120:123], v[16:31]
	ds_read_b128 v[218:221], v187 offset:29312
	v_add_f32_e32 v90, v106, v90
	v_add_f32_e32 v234, v234, v90
	v_add_f32_e32 v91, v107, v91
	v_add_f32_e32 v235, v235, v91
	v_add_f32_e32 v92, v108, v92
	v_add_f32_e32 v232, v232, v92
	s_waitcnt lgkmcnt(7)
	v_mfma_f32_32x32x16_bf16 v[32:47], v[226:229], v[120:123], v[32:47]
	ds_read_b128 v[222:225], v187 offset:29344
	v_add_f32_e32 v93, v109, v93
	v_add_f32_e32 v233, v233, v93
	v_add_f32_e32 v94, v110, v94
	v_add_f32_e32 v230, v230, v94
	s_waitcnt lgkmcnt(7)
	v_mfma_f32_32x32x16_bf16 v[48:63], v[128:131], v[164:167], v[0:15]
	ds_read_b128 v[226:229], v209 offset:35840
	v_exp_f32_e32 v64, v64
	v_exp_f32_e32 v65, v65
	v_exp_f32_e32 v66, v66
	s_waitcnt lgkmcnt(7)
	v_mfma_f32_32x32x16_bf16 v[48:63], v[132:135], v[144:147], v[48:63]
	ds_read_b128 v[128:131], v209 offset:40448
	v_exp_f32_e32 v67, v67
	v_exp_f32_e32 v68, v68
	v_exp_f32_e32 v69, v69
	s_waitcnt lgkmcnt(7)
	v_mfma_f32_32x32x16_bf16 v[48:63], v[136:139], v[148:151], v[48:63]
	ds_read_b128 v[132:135], v209 offset:35872
	v_exp_f32_e32 v70, v70
	v_exp_f32_e32 v71, v71
	v_cvt_pk_bf16_f32 v112, v64, v65
	v_cvt_pk_bf16_f32 v113, v66, v67
	s_waitcnt lgkmcnt(7)
	v_mfma_f32_32x32x16_bf16 v[16:31], v[140:143], v[124:127], v[16:31]
	ds_read_b128 v[136:139], v209 offset:40480
	v_cvt_pk_bf16_f32 v114, v68, v69
	v_cvt_pk_bf16_f32 v115, v70, v71
	v_exp_f32_e32 v72, v72
	v_exp_f32_e32 v73, v73
	s_waitcnt lgkmcnt(7)
	v_mfma_f32_32x32x16_bf16 v[32:47], v[188:191], v[124:127], v[32:47]
	v_exp_f32_e32 v74, v74
	v_exp_f32_e32 v75, v75
	v_exp_f32_e32 v76, v76
	s_waitcnt lgkmcnt(6)
	v_mfma_f32_32x32x16_bf16 v[48:63], v[168:171], v[152:155], v[48:63]
	v_exp_f32_e32 v77, v77
	v_exp_f32_e32 v78, v78
	v_exp_f32_e32 v79, v79
	s_waitcnt lgkmcnt(5)
	v_mfma_f32_32x32x16_bf16 v[48:63], v[218:221], v[156:159], v[48:63]
	v_cvt_pk_bf16_f32 v116, v72, v73
	v_cvt_pk_bf16_f32 v117, v74, v75
	v_cvt_pk_bf16_f32 v118, v76, v77
	v_cvt_pk_bf16_f32 v119, v78, v79
	s_waitcnt lgkmcnt(4)
	v_mfma_f32_32x32x16_bf16 v[48:63], v[222:225], v[160:163], v[48:63]
	v_add_f32_e32 v95, v111, v95
	v_add_f32_e32 v231, v231, v95
	s_waitcnt lgkmcnt(4)
	s_barrier
	ds_read_b128 v[140:143], v187 offset:45056
	ds_read_b128 v[188:191], v187 offset:45088
	ds_read_b128 v[168:171], v187 offset:45120
	ds_read_b128 v[218:221], v187 offset:45152
	s_waitcnt lgkmcnt(7)
	v_mfma_f32_32x32x16_bf16 v[16:31], v[226:229], v[112:115], v[16:31]
	ds_read_b128 v[222:225], v187 offset:45184
	s_waitcnt vmcnt(0)
	ds_write_b128 v211, v[176:179] offset:0
	s_and_saveexec_b64 s[42:43], s[36:37]
	s_cbranch_execz .Lattn_fx_w8
	ds_write_b128 v186, v[172:175] offset:0
.Lattn_fx_w8:
	s_or_b64 exec, exec, s[42:43]
	ds_write_b128 v208, v[180:183] offset:13312
	v_exp_f32_e32 v48, v48
	v_exp_f32_e32 v49, v49
	v_exp_f32_e32 v50, v50
	s_waitcnt lgkmcnt(9)
	v_mfma_f32_32x32x16_bf16 v[32:47], v[128:131], v[112:115], v[32:47]
	ds_read_b128 v[226:229], v187 offset:45216
	global_load_dwordx4 v[176:179], v212, s[6:7]
	s_and_saveexec_b64 s[42:43], s[36:37]
	s_cbranch_execz .Lattn_fx_g9
	global_load_dwordx4 v[172:175], v214, s[6:7]
.Lattn_fx_g9:
	s_or_b64 exec, exec, s[42:43]
	global_load_dwordx4 v[180:183], v204, s[40:41]
	s_add_u32 s6, s6, 0x18000
	s_addc_u32 s7, s7, 0
	s_add_u32 s40, s40, 0x80
	s_addc_u32 s41, s41, 0
	v_exp_f32_e32 v51, v51
	v_exp_f32_e32 v52, v52
	v_exp_f32_e32 v53, v53
	s_waitcnt lgkmcnt(9)
	v_mfma_f32_32x32x16_bf16 v[16:31], v[132:135], v[116:119], v[16:31]
	ds_read_b128 v[128:131], v209 offset:35904
	v_exp_f32_e32 v54, v54
	v_exp_f32_e32 v55, v55
	v_cvt_pk_bf16_f32 v120, v48, v49
	v_cvt_pk_bf16_f32 v121, v50, v51
	s_waitcnt lgkmcnt(9)
	v_mfma_f32_32x32x16_bf16 v[32:47], v[136:139], v[116:119], v[32:47]
	ds_read_b128 v[132:135], v209 offset:40512
	v_cvt_pk_bf16_f32 v122, v52, v53
	v_cvt_pk_bf16_f32 v123, v54, v55
	v_exp_f32_e32 v56, v56
	v_exp_f32_e32 v57, v57
	s_waitcnt lgkmcnt(9)
	v_mfma_f32_32x32x16_bf16 v[96:111], v[140:143], v[164:167], v[0:15]
	ds_read_b128 v[136:139], v187 offset:51712
	v_exp_f32_e32 v58, v58
	v_exp_f32_e32 v59, v59
	v_add_f32_e32 v48, v64, v48
	v_add_f32_e32 v244, v244, v48
	s_waitcnt lgkmcnt(9)
	v_mfma_f32_32x32x16_bf16 v[96:111], v[188:191], v[144:147], v[96:111]
	ds_read_b128 v[140:143], v187 offset:51744
	v_exp_f32_e32 v60, v60
	v_exp_f32_e32 v61, v61
	v_add_f32_e32 v49, v65, v49
	v_add_f32_e32 v245, v245, v49
	s_waitcnt lgkmcnt(9)
	v_mfma_f32_32x32x16_bf16 v[96:111], v[168:171], v[148:151], v[96:111]
	ds_read_b128 v[188:191], v187 offset:51776
	v_exp_f32_e32 v62, v62
	v_exp_f32_e32 v63, v63
	v_add_f32_e32 v50, v66, v50
	v_add_f32_e32 v242, v242, v50
	s_waitcnt lgkmcnt(9)
	v_mfma_f32_32x32x16_bf16 v[96:111], v[218:221], v[152:155], v[96:111]
	ds_read_b128 v[168:171], v209 offset:35936
	v_cvt_pk_bf16_f32 v124, v56, v57
	v_cvt_pk_bf16_f32 v125, v58, v59
	v_cvt_pk_bf16_f32 v126, v60, v61
	v_cvt_pk_bf16_f32 v127, v62, v63
	v_add_f32_e32 v51, v67, v51
	v_add_f32_e32 v243, v243, v51
	s_waitcnt lgkmcnt(9)
	v_mfma_f32_32x32x16_bf16 v[96:111], v[222:225], v[156:159], v[96:111]
	ds_read_b128 v[218:221], v209 offset:40544
	v_add_f32_e32 v52, v68, v52
	v_add_f32_e32 v240, v240, v52
	v_add_f32_e32 v53, v69, v53
	v_add_f32_e32 v241, v241, v53
	v_add_f32_e32 v54, v70, v54
	v_add_f32_e32 v238, v238, v54
	s_waitcnt lgkmcnt(7)
	v_mfma_f32_32x32x16_bf16 v[96:111], v[226:229], v[160:163], v[96:111]
	ds_read_b128 v[222:225], v187 offset:51808
	v_add_f32_e32 v55, v71, v55
	v_add_f32_e32 v239, v239, v55
	v_add_f32_e32 v56, v72, v56
	v_add_f32_e32 v236, v236, v56
	v_add_f32_e32 v57, v73, v57
	v_add_f32_e32 v237, v237, v57
	s_waitcnt lgkmcnt(7)
	v_mfma_f32_32x32x16_bf16 v[16:31], v[128:131], v[120:123], v[16:31]
	ds_read_b128 v[226:229], v187 offset:51840
	v_add_f32_e32 v58, v74, v58
	v_add_f32_e32 v234, v234, v58
	v_add_f32_e32 v59, v75, v59
	v_add_f32_e32 v235, v235, v59
	v_add_f32_e32 v60, v76, v60
	v_add_f32_e32 v232, v232, v60
	s_waitcnt lgkmcnt(7)
	v_mfma_f32_32x32x16_bf16 v[32:47], v[132:135], v[120:123], v[32:47]
	ds_read_b128 v[128:131], v187 offset:51872
	v_add_f32_e32 v61, v77, v61
	v_add_f32_e32 v233, v233, v61
	v_add_f32_e32 v62, v78, v62
	v_add_f32_e32 v230, v230, v62
	s_waitcnt lgkmcnt(7)
	v_mfma_f32_32x32x16_bf16 v[80:95], v[136:139], v[164:167], v[0:15]
	ds_read_b128 v[132:135], v209 offset:58368
	v_exp_f32_e32 v96, v96
	v_exp_f32_e32 v97, v97
	v_exp_f32_e32 v98, v98
	s_waitcnt lgkmcnt(7)
	v_mfma_f32_32x32x16_bf16 v[80:95], v[140:143], v[144:147], v[80:95]
	ds_read_b128 v[136:139], v209 offset:62976
	v_exp_f32_e32 v99, v99
	v_exp_f32_e32 v100, v100
	v_exp_f32_e32 v101, v101
	s_waitcnt lgkmcnt(7)
	v_mfma_f32_32x32x16_bf16 v[80:95], v[188:191], v[148:151], v[80:95]
	ds_read_b128 v[140:143], v209 offset:58400
	v_exp_f32_e32 v102, v102
	v_exp_f32_e32 v103, v103
	v_cvt_pk_bf16_f32 v112, v96, v97
	v_cvt_pk_bf16_f32 v113, v98, v99
	s_waitcnt lgkmcnt(7)
	v_mfma_f32_32x32x16_bf16 v[16:31], v[168:171], v[124:127], v[16:31]
	ds_read_b128 v[188:191], v209 offset:63008
	v_cvt_pk_bf16_f32 v114, v100, v101
	v_cvt_pk_bf16_f32 v115, v102, v103
	v_exp_f32_e32 v104, v104
	v_exp_f32_e32 v105, v105
	s_waitcnt lgkmcnt(7)
	v_mfma_f32_32x32x16_bf16 v[32:47], v[218:221], v[124:127], v[32:47]
	v_exp_f32_e32 v106, v106
	v_exp_f32_e32 v107, v107
	v_exp_f32_e32 v108, v108
	s_waitcnt lgkmcnt(6)
	v_mfma_f32_32x32x16_bf16 v[80:95], v[222:225], v[152:155], v[80:95]
	v_exp_f32_e32 v109, v109
	v_exp_f32_e32 v110, v110
	v_exp_f32_e32 v111, v111
	s_waitcnt lgkmcnt(5)
	v_mfma_f32_32x32x16_bf16 v[80:95], v[226:229], v[156:159], v[80:95]
	v_cvt_pk_bf16_f32 v116, v104, v105
	v_cvt_pk_bf16_f32 v117, v106, v107
	v_cvt_pk_bf16_f32 v118, v108, v109
	v_cvt_pk_bf16_f32 v119, v110, v111
	s_waitcnt lgkmcnt(4)
	v_mfma_f32_32x32x16_bf16 v[80:95], v[128:131], v[160:163], v[80:95]
	v_add_f32_e32 v63, v79, v63
	v_add_f32_e32 v231, v231, v63
	s_waitcnt lgkmcnt(4)
	s_barrier
	ds_read_b128 v[168:171], v187 offset:0
	ds_read_b128 v[218:221], v187 offset:32
	ds_read_b128 v[222:225], v187 offset:64
	ds_read_b128 v[226:229], v187 offset:96
	s_waitcnt lgkmcnt(7)
	v_mfma_f32_32x32x16_bf16 v[16:31], v[132:135], v[112:115], v[16:31]
	ds_read_b128 v[128:131], v187 offset:128
	s_waitcnt vmcnt(0)
	ds_write_b128 v211, v[176:179] offset:22528
	s_and_saveexec_b64 s[42:43], s[36:37]
	s_cbranch_execz .Lattn_fx_w10
	ds_write_b128 v186, v[172:175] offset:22528
.Lattn_fx_w10:
	s_or_b64 exec, exec, s[42:43]
	ds_write_b128 v208, v[180:183] offset:35840
	v_exp_f32_e32 v80, v80
	v_exp_f32_e32 v81, v81
	v_exp_f32_e32 v82, v82
	s_waitcnt lgkmcnt(9)
	v_mfma_f32_32x32x16_bf16 v[32:47], v[136:139], v[112:115], v[32:47]
	ds_read_b128 v[132:135], v187 offset:160
	global_load_dwordx4 v[176:179], v212, s[6:7]
	s_and_saveexec_b64 s[42:43], s[36:37]
	s_cbranch_execz .Lattn_fx_g11
	global_load_dwordx4 v[172:175], v214, s[6:7]
.Lattn_fx_g11:
	s_or_b64 exec, exec, s[42:43]
	global_load_dwordx4 v[180:183], v204, s[40:41]
	s_add_u32 s6, s6, 0x18000
	s_addc_u32 s7, s7, 0
	s_add_u32 s40, s40, 0x80
	s_addc_u32 s41, s41, 0
	v_exp_f32_e32 v83, v83
	v_exp_f32_e32 v84, v84
	v_exp_f32_e32 v85, v85
	s_waitcnt lgkmcnt(9)
	v_mfma_f32_32x32x16_bf16 v[16:31], v[140:143], v[116:119], v[16:31]
	ds_read_b128 v[136:139], v209 offset:58432
	v_exp_f32_e32 v86, v86
	v_exp_f32_e32 v87, v87
	v_cvt_pk_bf16_f32 v120, v80, v81
	v_cvt_pk_bf16_f32 v121, v82, v83
	s_waitcnt lgkmcnt(9)
	v_mfma_f32_32x32x16_bf16 v[32:47], v[188:191], v[116:119], v[32:47]
	ds_read_b128 v[140:143], v209 offset:63040
	v_cvt_pk_bf16_f32 v122, v84, v85
	v_cvt_pk_bf16_f32 v123, v86, v87
	v_exp_f32_e32 v88, v88
	v_exp_f32_e32 v89, v89
	s_waitcnt lgkmcnt(9)
	v_mfma_f32_32x32x16_bf16 v[64:79], v[168:171], v[164:167], v[0:15]
	ds_read_b128 v[188:191], v187 offset:6656
	v_exp_f32_e32 v90, v90
	v_exp_f32_e32 v91, v91
	v_add_f32_e32 v80, v96, v80
	v_add_f32_e32 v244, v244, v80
	s_waitcnt lgkmcnt(9)
	v_mfma_f32_32x32x16_bf16 v[64:79], v[218:221], v[144:147], v[64:79]
	ds_read_b128 v[168:171], v187 offset:6688
	v_exp_f32_e32 v92, v92
	v_exp_f32_e32 v93, v93
	v_add_f32_e32 v81, v97, v81
	v_add_f32_e32 v245, v245, v81
	s_waitcnt lgkmcnt(9)
	v_mfma_f32_32x32x16_bf16 v[64:79], v[222:225], v[148:151], v[64:79]
	ds_read_b128 v[218:221], v187 offset:6720
	v_exp_f32_e32 v94, v94
	v_exp_f32_e32 v95, v95
	v_add_f32_e32 v82, v98, v82
	v_add_f32_e32 v242, v242, v82
	s_waitcnt lgkmcnt(9)
	v_mfma_f32_32x32x16_bf16 v[64:79], v[226:229], v[152:155], v[64:79]
	ds_read_b128 v[222:225], v209 offset:58464
	v_cvt_pk_bf16_f32 v124, v88, v89
	v_cvt_pk_bf16_f32 v125, v90, v91
	v_cvt_pk_bf16_f32 v126, v92, v93
	v_cvt_pk_bf16_f32 v127, v94, v95
	v_add_f32_e32 v83, v99, v83
	v_add_f32_e32 v243, v243, v83
	s_waitcnt lgkmcnt(9)
	v_mfma_f32_32x32x16_bf16 v[64:79], v[128:131], v[156:159], v[64:79]
	ds_read_b128 v[226:229], v209 offset:63072
	v_add_f32_e32 v84, v100, v84
	v_add_f32_e32 v240, v240, v84
	v_add_f32_e32 v85, v101, v85
	v_add_f32_e32 v241, v241, v85
	v_add_f32_e32 v86, v102, v86
	v_add_f32_e32 v238, v238, v86
	s_waitcnt lgkmcnt(7)
	v_mfma_f32_32x32x16_bf16 v[64:79], v[132:135], v[160:163], v[64:79]
	ds_read_b128 v[128:131], v187 offset:6752
	v_add_f32_e32 v87, v103, v87
	v_add_f32_e32 v239, v239, v87
	v_add_f32_e32 v88, v104, v88
	v_add_f32_e32 v236, v236, v88
	v_add_f32_e32 v89, v105, v89
	v_add_f32_e32 v237, v237, v89
	s_waitcnt lgkmcnt(7)
	v_mfma_f32_32x32x16_bf16 v[16:31], v[136:139], v[120:123], v[16:31]
	ds_read_b128 v[132:135], v187 offset:6784
	v_add_f32_e32 v90, v106, v90
	v_add_f32_e32 v234, v234, v90
	v_add_f32_e32 v91, v107, v91
	v_add_f32_e32 v235, v235, v91
	v_add_f32_e32 v92, v108, v92
	v_add_f32_e32 v232, v232, v92
	s_waitcnt lgkmcnt(7)
	v_mfma_f32_32x32x16_bf16 v[32:47], v[140:143], v[120:123], v[32:47]
	ds_read_b128 v[136:139], v187 offset:6816
	v_add_f32_e32 v93, v109, v93
	v_add_f32_e32 v233, v233, v93
	v_add_f32_e32 v94, v110, v94
	v_add_f32_e32 v230, v230, v94
	s_waitcnt lgkmcnt(7)
	v_mfma_f32_32x32x16_bf16 v[48:63], v[188:191], v[164:167], v[0:15]
	ds_read_b128 v[140:143], v209 offset:13312
	v_exp_f32_e32 v64, v64
	v_exp_f32_e32 v65, v65
	v_exp_f32_e32 v66, v66
	s_waitcnt lgkmcnt(7)
	v_mfma_f32_32x32x16_bf16 v[48:63], v[168:171], v[144:147], v[48:63]
	ds_read_b128 v[188:191], v209 offset:17920
	v_exp_f32_e32 v67, v67
	v_exp_f32_e32 v68, v68
	v_exp_f32_e32 v69, v69
	s_waitcnt lgkmcnt(7)
	v_mfma_f32_32x32x16_bf16 v[48:63], v[218:221], v[148:151], v[48:63]
	ds_read_b128 v[168:171], v209 offset:13344
	v_exp_f32_e32 v70, v70
	v_exp_f32_e32 v71, v71
	v_cvt_pk_bf16_f32 v112, v64, v65
	v_cvt_pk_bf16_f32 v113, v66, v67
	s_waitcnt lgkmcnt(7)
	v_mfma_f32_32x32x16_bf16 v[16:31], v[222:225], v[124:127], v[16:31]
	ds_read_b128 v[218:221], v209 offset:17952
	v_cvt_pk_bf16_f32 v114, v68, v69
	v_cvt_pk_bf16_f32 v115, v70, v71
	v_exp_f32_e32 v72, v72
	v_exp_f32_e32 v73, v73
	s_waitcnt lgkmcnt(7)
	v_mfma_f32_32x32x16_bf16 v[32:47], v[226:229], v[124:127], v[32:47]
	v_exp_f32_e32 v74, v74
	v_exp_f32_e32 v75, v75
	v_exp_f32_e32 v76, v76
	s_waitcnt lgkmcnt(6)
	v_mfma_f32_32x32x16_bf16 v[48:63], v[128:131], v[152:155], v[48:63]
	v_exp_f32_e32 v77, v77
	v_exp_f32_e32 v78, v78
	v_exp_f32_e32 v79, v79
	s_waitcnt lgkmcnt(5)
	v_mfma_f32_32x32x16_bf16 v[48:63], v[132:135], v[156:159], v[48:63]
	v_cvt_pk_bf16_f32 v116, v72, v73
	v_cvt_pk_bf16_f32 v117, v74, v75
	v_cvt_pk_bf16_f32 v118, v76, v77
	v_cvt_pk_bf16_f32 v119, v78, v79
	s_waitcnt lgkmcnt(4)
	v_mfma_f32_32x32x16_bf16 v[48:63], v[136:139], v[160:163], v[48:63]
	v_add_f32_e32 v95, v111, v95
	v_add_f32_e32 v231, v231, v95
	s_waitcnt lgkmcnt(4)
	s_barrier
	ds_read_b128 v[222:225], v187 offset:22528
	ds_read_b128 v[226:229], v187 offset:22560
	ds_read_b128 v[128:131], v187 offset:22592
	ds_read_b128 v[132:135], v187 offset:22624
	s_waitcnt lgkmcnt(7)
	v_mfma_f32_32x32x16_bf16 v[16:31], v[140:143], v[112:115], v[16:31]
	ds_read_b128 v[136:139], v187 offset:22656
	s_waitcnt vmcnt(0)
	ds_write_b128 v211, v[176:179] offset:45056
	s_and_saveexec_b64 s[42:43], s[36:37]
	s_cbranch_execz .Lattn_fx_w12
	ds_write_b128 v186, v[172:175] offset:45056
.Lattn_fx_w12:
	s_or_b64 exec, exec, s[42:43]
	ds_write_b128 v208, v[180:183] offset:58368
	v_exp_f32_e32 v48, v48
	v_exp_f32_e32 v49, v49
	v_exp_f32_e32 v50, v50
	s_waitcnt lgkmcnt(9)
	v_mfma_f32_32x32x16_bf16 v[32:47], v[188:191], v[112:115], v[32:47]
	ds_read_b128 v[140:143], v187 offset:22688
	global_load_dwordx4 v[176:179], v212, s[6:7]
	s_and_saveexec_b64 s[42:43], s[36:37]
	s_cbranch_execz .Lattn_fx_g13
	global_load_dwordx4 v[172:175], v214, s[6:7]
.Lattn_fx_g13:
	s_or_b64 exec, exec, s[42:43]
	global_load_dwordx4 v[180:183], v204, s[40:41]
	s_add_u32 s6, s6, 0x18000
	s_addc_u32 s7, s7, 0
	s_add_u32 s40, s40, 0x80
	s_addc_u32 s41, s41, 0
	v_exp_f32_e32 v51, v51
	v_exp_f32_e32 v52, v52
	v_exp_f32_e32 v53, v53
	s_waitcnt lgkmcnt(9)
	v_mfma_f32_32x32x16_bf16 v[16:31], v[168:171], v[116:119], v[16:31]
	ds_read_b128 v[188:191], v209 offset:13376
	v_exp_f32_e32 v54, v54
	v_exp_f32_e32 v55, v55
	v_cvt_pk_bf16_f32 v120, v48, v49
	v_cvt_pk_bf16_f32 v121, v50, v51
	s_waitcnt lgkmcnt(9)
	v_mfma_f32_32x32x16_bf16 v[32:47], v[218:221], v[116:119], v[32:47]
	ds_read_b128 v[168:171], v209 offset:17984
	v_cvt_pk_bf16_f32 v122, v52, v53
	v_cvt_pk_bf16_f32 v123, v54, v55
	v_exp_f32_e32 v56, v56
	v_exp_f32_e32 v57, v57
	s_waitcnt lgkmcnt(9)
	v_mfma_f32_32x32x16_bf16 v[96:111], v[222:225], v[164:167], v[0:15]
	ds_read_b128 v[218:221], v187 offset:29184
	v_exp_f32_e32 v58, v58
	v_exp_f32_e32 v59, v59
	v_add_f32_e32 v48, v64, v48
	v_add_f32_e32 v244, v244, v48
	s_waitcnt lgkmcnt(9)
	v_mfma_f32_32x32x16_bf16 v[96:111], v[226:229], v[144:147], v[96:111]
	ds_read_b128 v[222:225], v187 offset:29216
	v_exp_f32_e32 v60, v60
	v_exp_f32_e32 v61, v61
	v_add_f32_e32 v49, v65, v49
	v_add_f32_e32 v245, v245, v49
	s_waitcnt lgkmcnt(9)
	v_mfma_f32_32x32x16_bf16 v[96:111], v[128:131], v[148:151], v[96:111]
	ds_read_b128 v[226:229], v187 offset:29248
	v_exp_f32_e32 v62, v62
	v_exp_f32_e32 v63, v63
	v_add_f32_e32 v50, v66, v50
	v_add_f32_e32 v242, v242, v50
	s_waitcnt lgkmcnt(9)
	v_mfma_f32_32x32x16_bf16 v[96:111], v[132:135], v[152:155], v[96:111]
	ds_read_b128 v[128:131], v209 offset:13408
	v_cvt_pk_bf16_f32 v124, v56, v57
	v_cvt_pk_bf16_f32 v125, v58, v59
	v_cvt_pk_bf16_f32 v126, v60, v61
	v_cvt_pk_bf16_f32 v127, v62, v63
	v_add_f32_e32 v51, v67, v51
	v_add_f32_e32 v243, v243, v51
	s_waitcnt lgkmcnt(9)
	v_mfma_f32_32x32x16_bf16 v[96:111], v[136:139], v[156:159], v[96:111]
	ds_read_b128 v[132:135], v209 offset:18016
	v_add_f32_e32 v52, v68, v52
	v_add_f32_e32 v240, v240, v52
	v_add_f32_e32 v53, v69, v53
	v_add_f32_e32 v241, v241, v53
	v_add_f32_e32 v54, v70, v54
	v_add_f32_e32 v238, v238, v54
	s_waitcnt lgkmcnt(7)
	v_mfma_f32_32x32x16_bf16 v[96:111], v[140:143], v[160:163], v[96:111]
	ds_read_b128 v[136:139], v187 offset:29280
	v_add_f32_e32 v55, v71, v55
	v_add_f32_e32 v239, v239, v55
	v_add_f32_e32 v56, v72, v56
	v_add_f32_e32 v236, v236, v56
	v_add_f32_e32 v57, v73, v57
	v_add_f32_e32 v237, v237, v57
	s_waitcnt lgkmcnt(7)
	v_mfma_f32_32x32x16_bf16 v[16:31], v[188:191], v[120:123], v[16:31]
	ds_read_b128 v[140:143], v187 offset:29312
	v_add_f32_e32 v58, v74, v58
	v_add_f32_e32 v234, v234, v58
	v_add_f32_e32 v59, v75, v59
	v_add_f32_e32 v235, v235, v59
	v_add_f32_e32 v60, v76, v60
	v_add_f32_e32 v232, v232, v60
	s_waitcnt lgkmcnt(7)
	v_mfma_f32_32x32x16_bf16 v[32:47], v[168:171], v[120:123], v[32:47]
	ds_read_b128 v[188:191], v187 offset:29344
	v_add_f32_e32 v61, v77, v61
	v_add_f32_e32 v233, v233, v61
	v_add_f32_e32 v62, v78, v62
	v_add_f32_e32 v230, v230, v62
	s_waitcnt lgkmcnt(7)
	v_mfma_f32_32x32x16_bf16 v[80:95], v[218:221], v[164:167], v[0:15]
	ds_read_b128 v[168:171], v209 offset:35840
	v_exp_f32_e32 v96, v96
	v_exp_f32_e32 v97, v97
	v_exp_f32_e32 v98, v98
	s_waitcnt lgkmcnt(7)
	v_mfma_f32_32x32x16_bf16 v[80:95], v[222:225], v[144:147], v[80:95]
	ds_read_b128 v[218:221], v209 offset:40448
	v_exp_f32_e32 v99, v99
	v_exp_f32_e32 v100, v100
	v_exp_f32_e32 v101, v101
	s_waitcnt lgkmcnt(7)
	v_mfma_f32_32x32x16_bf16 v[80:95], v[226:229], v[148:151], v[80:95]
	ds_read_b128 v[222:225], v209 offset:35872
	v_exp_f32_e32 v102, v102
	v_exp_f32_e32 v103, v103
	v_cvt_pk_bf16_f32 v112, v96, v97
	v_cvt_pk_bf16_f32 v113, v98, v99
	s_waitcnt lgkmcnt(7)
	v_mfma_f32_32x32x16_bf16 v[16:31], v[128:131], v[124:127], v[16:31]
	ds_read_b128 v[226:229], v209 offset:40480
	v_cvt_pk_bf16_f32 v114, v100, v101
	v_cvt_pk_bf16_f32 v115, v102, v103
	v_exp_f32_e32 v104, v104
	v_exp_f32_e32 v105, v105
	s_waitcnt lgkmcnt(7)
	v_mfma_f32_32x32x16_bf16 v[32:47], v[132:135], v[124:127], v[32:47]
	v_exp_f32_e32 v106, v106
	v_exp_f32_e32 v107, v107
	v_exp_f32_e32 v108, v108
	s_waitcnt lgkmcnt(6)
	v_mfma_f32_32x32x16_bf16 v[80:95], v[136:139], v[152:155], v[80:95]
	v_exp_f32_e32 v109, v109
	v_exp_f32_e32 v110, v110
	v_exp_f32_e32 v111, v111
	s_waitcnt lgkmcnt(5)
	v_mfma_f32_32x32x16_bf16 v[80:95], v[140:143], v[156:159], v[80:95]
	v_cvt_pk_bf16_f32 v116, v104, v105
	v_cvt_pk_bf16_f32 v117, v106, v107
	v_cvt_pk_bf16_f32 v118, v108, v109
	v_cvt_pk_bf16_f32 v119, v110, v111
	s_waitcnt lgkmcnt(4)
	v_mfma_f32_32x32x16_bf16 v[80:95], v[188:191], v[160:163], v[80:95]
	v_add_f32_e32 v63, v79, v63
	v_add_f32_e32 v231, v231, v63
	s_waitcnt lgkmcnt(4)
	s_barrier
	ds_read_b128 v[128:131], v187 offset:45056
	ds_read_b128 v[132:135], v187 offset:45088
	ds_read_b128 v[136:139], v187 offset:45120
	ds_read_b128 v[140:143], v187 offset:45152
	s_waitcnt lgkmcnt(7)
	v_mfma_f32_32x32x16_bf16 v[16:31], v[168:171], v[112:115], v[16:31]
	ds_read_b128 v[188:191], v187 offset:45184
	s_waitcnt vmcnt(0)
	ds_write_b128 v211, v[176:179] offset:0
	s_and_saveexec_b64 s[42:43], s[36:37]
	s_cbranch_execz .Lattn_fx_w14
	ds_write_b128 v186, v[172:175] offset:0
.Lattn_fx_w14:
	s_or_b64 exec, exec, s[42:43]
	ds_write_b128 v208, v[180:183] offset:13312
	v_exp_f32_e32 v80, v80
	v_exp_f32_e32 v81, v81
	v_exp_f32_e32 v82, v82
	s_waitcnt lgkmcnt(9)
	v_mfma_f32_32x32x16_bf16 v[32:47], v[218:221], v[112:115], v[32:47]
	ds_read_b128 v[168:171], v187 offset:45216
	global_load_dwordx4 v[176:179], v212, s[6:7]
	s_and_saveexec_b64 s[42:43], s[36:37]
	s_cbranch_execz .Lattn_fx_g15
	global_load_dwordx4 v[172:175], v214, s[6:7]
.Lattn_fx_g15:
	s_or_b64 exec, exec, s[42:43]
	global_load_dwordx4 v[180:183], v204, s[40:41]
	s_add_u32 s6, s6, 0x18000
	s_addc_u32 s7, s7, 0
	s_add_u32 s40, s40, 0x80
	s_addc_u32 s41, s41, 0
	v_exp_f32_e32 v83, v83
	v_exp_f32_e32 v84, v84
	v_exp_f32_e32 v85, v85
	s_waitcnt lgkmcnt(9)
	v_mfma_f32_32x32x16_bf16 v[16:31], v[222:225], v[116:119], v[16:31]
	ds_read_b128 v[218:221], v209 offset:35904
	v_exp_f32_e32 v86, v86
	v_exp_f32_e32 v87, v87
	v_cvt_pk_bf16_f32 v120, v80, v81
	v_cvt_pk_bf16_f32 v121, v82, v83
	s_waitcnt lgkmcnt(9)
	v_mfma_f32_32x32x16_bf16 v[32:47], v[226:229], v[116:119], v[32:47]
	ds_read_b128 v[222:225], v209 offset:40512
	v_cvt_pk_bf16_f32 v122, v84, v85
	v_cvt_pk_bf16_f32 v123, v86, v87
	v_exp_f32_e32 v88, v88
	v_exp_f32_e32 v89, v89
	s_waitcnt lgkmcnt(9)
	v_mfma_f32_32x32x16_bf16 v[64:79], v[128:131], v[164:167], v[0:15]
	ds_read_b128 v[226:229], v187 offset:51712
	v_exp_f32_e32 v90, v90
	v_exp_f32_e32 v91, v91
	v_add_f32_e32 v80, v96, v80
	v_add_f32_e32 v244, v244, v80
	s_waitcnt lgkmcnt(9)
	v_mfma_f32_32x32x16_bf16 v[64:79], v[132:135], v[144:147], v[64:79]
	ds_read_b128 v[128:131], v187 offset:51744
	v_exp_f32_e32 v92, v92
	v_exp_f32_e32 v93, v93
	v_add_f32_e32 v81, v97, v81
	v_add_f32_e32 v245, v245, v81
	s_waitcnt lgkmcnt(9)
	v_mfma_f32_32x32x16_bf16 v[64:79], v[136:139], v[148:151], v[64:79]
	ds_read_b128 v[132:135], v187 offset:51776
	v_exp_f32_e32 v94, v94
	v_exp_f32_e32 v95, v95
	v_add_f32_e32 v82, v98, v82
	v_add_f32_e32 v242, v242, v82
	s_waitcnt lgkmcnt(9)
	v_mfma_f32_32x32x16_bf16 v[64:79], v[140:143], v[152:155], v[64:79]
	ds_read_b128 v[136:139], v209 offset:35936
	v_cvt_pk_bf16_f32 v124, v88, v89
	v_cvt_pk_bf16_f32 v125, v90, v91
	v_cvt_pk_bf16_f32 v126, v92, v93
	v_cvt_pk_bf16_f32 v127, v94, v95
	v_add_f32_e32 v83, v99, v83
	v_add_f32_e32 v243, v243, v83
	s_waitcnt lgkmcnt(9)
	v_mfma_f32_32x32x16_bf16 v[64:79], v[188:191], v[156:159], v[64:79]
	ds_read_b128 v[140:143], v209 offset:40544
	v_add_f32_e32 v84, v100, v84
	v_add_f32_e32 v240, v240, v84
	v_add_f32_e32 v85, v101, v85
	v_add_f32_e32 v241, v241, v85
	v_add_f32_e32 v86, v102, v86
	v_add_f32_e32 v238, v238, v86
	s_waitcnt lgkmcnt(7)
	v_mfma_f32_32x32x16_bf16 v[64:79], v[168:171], v[160:163], v[64:79]
	ds_read_b128 v[188:191], v187 offset:51808
	v_add_f32_e32 v87, v103, v87
	v_add_f32_e32 v239, v239, v87
	v_add_f32_e32 v88, v104, v88
	v_add_f32_e32 v236, v236, v88
	v_add_f32_e32 v89, v105, v89
	v_add_f32_e32 v237, v237, v89
	s_waitcnt lgkmcnt(7)
	v_mfma_f32_32x32x16_bf16 v[16:31], v[218:221], v[120:123], v[16:31]
	ds_read_b128 v[168:171], v187 offset:51840
	v_add_f32_e32 v90, v106, v90
	v_add_f32_e32 v234, v234, v90
	v_add_f32_e32 v91, v107, v91
	v_add_f32_e32 v235, v235, v91
	v_add_f32_e32 v92, v108, v92
	v_add_f32_e32 v232, v232, v92
	s_waitcnt lgkmcnt(7)
	v_mfma_f32_32x32x16_bf16 v[32:47], v[222:225], v[120:123], v[32:47]
	ds_read_b128 v[218:221], v187 offset:51872
	v_add_f32_e32 v93, v109, v93
	v_add_f32_e32 v233, v233, v93
	v_add_f32_e32 v94, v110, v94
	v_add_f32_e32 v230, v230, v94
	s_waitcnt lgkmcnt(7)
	v_mfma_f32_32x32x16_bf16 v[48:63], v[226:229], v[164:167], v[0:15]
	ds_read_b128 v[222:225], v209 offset:58368
	v_exp_f32_e32 v64, v64
	v_exp_f32_e32 v65, v65
	v_exp_f32_e32 v66, v66
	s_waitcnt lgkmcnt(7)
	v_mfma_f32_32x32x16_bf16 v[48:63], v[128:131], v[144:147], v[48:63]
	ds_read_b128 v[226:229], v209 offset:62976
	v_exp_f32_e32 v67, v67
	v_exp_f32_e32 v68, v68
	v_exp_f32_e32 v69, v69
	s_waitcnt lgkmcnt(7)
	v_mfma_f32_32x32x16_bf16 v[48:63], v[132:135], v[148:151], v[48:63]
	ds_read_b128 v[128:131], v209 offset:58400
	v_exp_f32_e32 v70, v70
	v_exp_f32_e32 v71, v71
	v_cvt_pk_bf16_f32 v112, v64, v65
	v_cvt_pk_bf16_f32 v113, v66, v67
	s_waitcnt lgkmcnt(7)
	v_mfma_f32_32x32x16_bf16 v[16:31], v[136:139], v[124:127], v[16:31]
	ds_read_b128 v[132:135], v209 offset:63008
	v_cvt_pk_bf16_f32 v114, v68, v69
	v_cvt_pk_bf16_f32 v115, v70, v71
	v_exp_f32_e32 v72, v72
	v_exp_f32_e32 v73, v73
	s_waitcnt lgkmcnt(7)
	v_mfma_f32_32x32x16_bf16 v[32:47], v[140:143], v[124:127], v[32:47]
	v_exp_f32_e32 v74, v74
	v_exp_f32_e32 v75, v75
	v_exp_f32_e32 v76, v76
	s_waitcnt lgkmcnt(6)
	v_mfma_f32_32x32x16_bf16 v[48:63], v[188:191], v[152:155], v[48:63]
	v_exp_f32_e32 v77, v77
	v_exp_f32_e32 v78, v78
	v_exp_f32_e32 v79, v79
	s_waitcnt lgkmcnt(5)
	v_mfma_f32_32x32x16_bf16 v[48:63], v[168:171], v[156:159], v[48:63]
	v_cvt_pk_bf16_f32 v116, v72, v73
	v_cvt_pk_bf16_f32 v117, v74, v75
	v_cvt_pk_bf16_f32 v118, v76, v77
	v_cvt_pk_bf16_f32 v119, v78, v79
	s_waitcnt lgkmcnt(4)
	v_mfma_f32_32x32x16_bf16 v[48:63], v[218:221], v[160:163], v[48:63]
	v_add_f32_e32 v95, v111, v95
	v_add_f32_e32 v231, v231, v95
	s_waitcnt lgkmcnt(4)
	s_barrier
	ds_read_b128 v[136:139], v187 offset:0
	ds_read_b128 v[140:143], v187 offset:32
	ds_read_b128 v[188:191], v187 offset:64
	ds_read_b128 v[168:171], v187 offset:96
	s_waitcnt lgkmcnt(7)
	v_mfma_f32_32x32x16_bf16 v[16:31], v[222:225], v[112:115], v[16:31]
	ds_read_b128 v[218:221], v187 offset:128
	s_waitcnt vmcnt(0)
	ds_write_b128 v211, v[176:179] offset:22528
	s_and_saveexec_b64 s[42:43], s[36:37]
	s_cbranch_execz .Lattn_fx_w16
	ds_write_b128 v186, v[172:175] offset:22528
.Lattn_fx_w16:
	s_or_b64 exec, exec, s[42:43]
	ds_write_b128 v208, v[180:183] offset:35840
	v_exp_f32_e32 v48, v48
	v_exp_f32_e32 v49, v49
	v_exp_f32_e32 v50, v50
	s_waitcnt lgkmcnt(9)
	v_mfma_f32_32x32x16_bf16 v[32:47], v[226:229], v[112:115], v[32:47]
	ds_read_b128 v[222:225], v187 offset:160
	global_load_dwordx4 v[176:179], v212, s[6:7]
	s_and_saveexec_b64 s[42:43], s[36:37]
	s_cbranch_execz .Lattn_fx_g17
	global_load_dwordx4 v[172:175], v214, s[6:7]
.Lattn_fx_g17:
	s_or_b64 exec, exec, s[42:43]
	global_load_dwordx4 v[180:183], v204, s[40:41]
	s_add_u32 s6, s6, 0x18000
	s_addc_u32 s7, s7, 0
	s_add_u32 s40, s40, 0x80
	s_addc_u32 s41, s41, 0
	v_exp_f32_e32 v51, v51
	v_exp_f32_e32 v52, v52
	v_exp_f32_e32 v53, v53
	s_waitcnt lgkmcnt(9)
	v_mfma_f32_32x32x16_bf16 v[16:31], v[128:131], v[116:119], v[16:31]
	ds_read_b128 v[226:229], v209 offset:58432
	v_exp_f32_e32 v54, v54
	v_exp_f32_e32 v55, v55
	v_cvt_pk_bf16_f32 v120, v48, v49
	v_cvt_pk_bf16_f32 v121, v50, v51
	s_waitcnt lgkmcnt(9)
	v_mfma_f32_32x32x16_bf16 v[32:47], v[132:135], v[116:119], v[32:47]
	ds_read_b128 v[128:131], v209 offset:63040
	v_cvt_pk_bf16_f32 v122, v52, v53
	v_cvt_pk_bf16_f32 v123, v54, v55
	v_exp_f32_e32 v56, v56
	v_exp_f32_e32 v57, v57
	s_waitcnt lgkmcnt(9)
	v_mfma_f32_32x32x16_bf16 v[96:111], v[136:139], v[164:167], v[0:15]
	ds_read_b128 v[132:135], v187 offset:6656
	v_exp_f32_e32 v58, v58
	v_exp_f32_e32 v59, v59
	v_add_f32_e32 v48, v64, v48
	v_add_f32_e32 v244, v244, v48
	s_waitcnt lgkmcnt(9)
	v_mfma_f32_32x32x16_bf16 v[96:111], v[140:143], v[144:147], v[96:111]
	ds_read_b128 v[136:139], v187 offset:6688
	v_exp_f32_e32 v60, v60
	v_exp_f32_e32 v61, v61
	v_add_f32_e32 v49, v65, v49
	v_add_f32_e32 v245, v245, v49
	s_waitcnt lgkmcnt(9)
	v_mfma_f32_32x32x16_bf16 v[96:111], v[188:191], v[148:151], v[96:111]
	ds_read_b128 v[140:143], v187 offset:6720
	v_exp_f32_e32 v62, v62
	v_exp_f32_e32 v63, v63
	v_add_f32_e32 v50, v66, v50
	v_add_f32_e32 v242, v242, v50
	s_waitcnt lgkmcnt(9)
	v_mfma_f32_32x32x16_bf16 v[96:111], v[168:171], v[152:155], v[96:111]
	ds_read_b128 v[188:191], v209 offset:58464
	v_cvt_pk_bf16_f32 v124, v56, v57
	v_cvt_pk_bf16_f32 v125, v58, v59
	v_cvt_pk_bf16_f32 v126, v60, v61
	v_cvt_pk_bf16_f32 v127, v62, v63
	v_add_f32_e32 v51, v67, v51
	v_add_f32_e32 v243, v243, v51
	s_waitcnt lgkmcnt(9)
	v_mfma_f32_32x32x16_bf16 v[96:111], v[218:221], v[156:159], v[96:111]
	ds_read_b128 v[168:171], v209 offset:63072
	v_add_f32_e32 v52, v68, v52
	v_add_f32_e32 v240, v240, v52
	v_add_f32_e32 v53, v69, v53
	v_add_f32_e32 v241, v241, v53
	v_add_f32_e32 v54, v70, v54
	v_add_f32_e32 v238, v238, v54
	s_waitcnt lgkmcnt(7)
	v_mfma_f32_32x32x16_bf16 v[96:111], v[222:225], v[160:163], v[96:111]
	ds_read_b128 v[218:221], v187 offset:6752
	v_add_f32_e32 v55, v71, v55
	v_add_f32_e32 v239, v239, v55
	v_add_f32_e32 v56, v72, v56
	v_add_f32_e32 v236, v236, v56
	v_add_f32_e32 v57, v73, v57
	v_add_f32_e32 v237, v237, v57
	s_waitcnt lgkmcnt(7)
	v_mfma_f32_32x32x16_bf16 v[16:31], v[226:229], v[120:123], v[16:31]
	ds_read_b128 v[222:225], v187 offset:6784
	v_add_f32_e32 v58, v74, v58
	v_add_f32_e32 v234, v234, v58
	v_add_f32_e32 v59, v75, v59
	v_add_f32_e32 v235, v235, v59
	v_add_f32_e32 v60, v76, v60
	v_add_f32_e32 v232, v232, v60
	s_waitcnt lgkmcnt(7)
	v_mfma_f32_32x32x16_bf16 v[32:47], v[128:131], v[120:123], v[32:47]
	ds_read_b128 v[226:229], v187 offset:6816
	v_add_f32_e32 v61, v77, v61
	v_add_f32_e32 v233, v233, v61
	v_add_f32_e32 v62, v78, v62
	v_add_f32_e32 v230, v230, v62
	s_waitcnt lgkmcnt(7)
	v_mfma_f32_32x32x16_bf16 v[80:95], v[132:135], v[164:167], v[0:15]
	ds_read_b128 v[128:131], v209 offset:13312
	v_exp_f32_e32 v96, v96
	v_exp_f32_e32 v97, v97
	v_exp_f32_e32 v98, v98
	s_waitcnt lgkmcnt(7)
	v_mfma_f32_32x32x16_bf16 v[80:95], v[136:139], v[144:147], v[80:95]
	ds_read_b128 v[132:135], v209 offset:17920
	v_exp_f32_e32 v99, v99
	v_exp_f32_e32 v100, v100
	v_exp_f32_e32 v101, v101
	s_waitcnt lgkmcnt(7)
	v_mfma_f32_32x32x16_bf16 v[80:95], v[140:143], v[148:151], v[80:95]
	ds_read_b128 v[136:139], v209 offset:13344
	v_exp_f32_e32 v102, v102
	v_exp_f32_e32 v103, v103
	v_cvt_pk_bf16_f32 v112, v96, v97
	v_cvt_pk_bf16_f32 v113, v98, v99
	s_waitcnt lgkmcnt(7)
	v_mfma_f32_32x32x16_bf16 v[16:31], v[188:191], v[124:127], v[16:31]
	ds_read_b128 v[140:143], v209 offset:17952
	v_cvt_pk_bf16_f32 v114, v100, v101
	v_cvt_pk_bf16_f32 v115, v102, v103
	v_exp_f32_e32 v104, v104
	v_exp_f32_e32 v105, v105
	s_waitcnt lgkmcnt(7)
	v_mfma_f32_32x32x16_bf16 v[32:47], v[168:171], v[124:127], v[32:47]
	v_exp_f32_e32 v106, v106
	v_exp_f32_e32 v107, v107
	v_exp_f32_e32 v108, v108
	s_waitcnt lgkmcnt(6)
	v_mfma_f32_32x32x16_bf16 v[80:95], v[218:221], v[152:155], v[80:95]
	v_exp_f32_e32 v109, v109
	v_exp_f32_e32 v110, v110
	v_exp_f32_e32 v111, v111
	s_waitcnt lgkmcnt(5)
	v_mfma_f32_32x32x16_bf16 v[80:95], v[222:225], v[156:159], v[80:95]
	v_cvt_pk_bf16_f32 v116, v104, v105
	v_cvt_pk_bf16_f32 v117, v106, v107
	v_cvt_pk_bf16_f32 v118, v108, v109
	v_cvt_pk_bf16_f32 v119, v110, v111
	s_waitcnt lgkmcnt(4)
	v_mfma_f32_32x32x16_bf16 v[80:95], v[226:229], v[160:163], v[80:95]
	v_add_f32_e32 v63, v79, v63
	v_add_f32_e32 v231, v231, v63
	s_waitcnt lgkmcnt(4)
	s_barrier
	ds_read_b128 v[188:191], v187 offset:22528
	ds_read_b128 v[168:171], v187 offset:22560
	ds_read_b128 v[218:221], v187 offset:22592
	ds_read_b128 v[222:225], v187 offset:22624
	s_waitcnt lgkmcnt(7)
	v_mfma_f32_32x32x16_bf16 v[16:31], v[128:131], v[112:115], v[16:31]
	ds_read_b128 v[226:229], v187 offset:22656
	s_waitcnt vmcnt(0)
	ds_write_b128 v211, v[176:179] offset:45056
	s_and_saveexec_b64 s[42:43], s[36:37]
	s_cbranch_execz .Lattn_fx_w18
	ds_write_b128 v186, v[172:175] offset:45056
.Lattn_fx_w18:
	s_or_b64 exec, exec, s[42:43]
	ds_write_b128 v208, v[180:183] offset:58368
	v_exp_f32_e32 v80, v80
	v_exp_f32_e32 v81, v81
	v_exp_f32_e32 v82, v82
	s_waitcnt lgkmcnt(9)
	v_mfma_f32_32x32x16_bf16 v[32:47], v[132:135], v[112:115], v[32:47]
	ds_read_b128 v[128:131], v187 offset:22688
	global_load_dwordx4 v[176:179], v212, s[6:7]
	s_and_saveexec_b64 s[42:43], s[36:37]
	s_cbranch_execz .Lattn_fx_g19
	global_load_dwordx4 v[172:175], v214, s[6:7]
.Lattn_fx_g19:
	s_or_b64 exec, exec, s[42:43]
	global_load_dwordx4 v[180:183], v204, s[40:41]
	s_add_u32 s6, s6, 0x18000
	s_addc_u32 s7, s7, 0
	s_add_u32 s40, s40, 0x80
	s_addc_u32 s41, s41, 0
	v_exp_f32_e32 v83, v83
	v_exp_f32_e32 v84, v84
	v_exp_f32_e32 v85, v85
	s_waitcnt lgkmcnt(9)
	v_mfma_f32_32x32x16_bf16 v[16:31], v[136:139], v[116:119], v[16:31]
	ds_read_b128 v[132:135], v209 offset:13376
	v_exp_f32_e32 v86, v86
	v_exp_f32_e32 v87, v87
	v_cvt_pk_bf16_f32 v120, v80, v81
	v_cvt_pk_bf16_f32 v121, v82, v83
	s_waitcnt lgkmcnt(9)
	v_mfma_f32_32x32x16_bf16 v[32:47], v[140:143], v[116:119], v[32:47]
	ds_read_b128 v[136:139], v209 offset:17984
	v_cvt_pk_bf16_f32 v122, v84, v85
	v_cvt_pk_bf16_f32 v123, v86, v87
	v_exp_f32_e32 v88, v88
	v_exp_f32_e32 v89, v89
	s_waitcnt lgkmcnt(9)
	v_mfma_f32_32x32x16_bf16 v[64:79], v[188:191], v[164:167], v[0:15]
	ds_read_b128 v[140:143], v187 offset:29184
	v_exp_f32_e32 v90, v90
	v_exp_f32_e32 v91, v91
	v_add_f32_e32 v80, v96, v80
	v_add_f32_e32 v244, v244, v80
	s_waitcnt lgkmcnt(9)
	v_mfma_f32_32x32x16_bf16 v[64:79], v[168:171], v[144:147], v[64:79]
	ds_read_b128 v[188:191], v187 offset:29216
	v_exp_f32_e32 v92, v92
	v_exp_f32_e32 v93, v93
	v_add_f32_e32 v81, v97, v81
	v_add_f32_e32 v245, v245, v81
	s_waitcnt lgkmcnt(9)
	v_mfma_f32_32x32x16_bf16 v[64:79], v[218:221], v[148:151], v[64:79]
	ds_read_b128 v[168:171], v187 offset:29248
	v_exp_f32_e32 v94, v94
	v_exp_f32_e32 v95, v95
	v_add_f32_e32 v82, v98, v82
	v_add_f32_e32 v242, v242, v82
	s_waitcnt lgkmcnt(9)
	v_mfma_f32_32x32x16_bf16 v[64:79], v[222:225], v[152:155], v[64:79]
	ds_read_b128 v[218:221], v209 offset:13408
	v_cvt_pk_bf16_f32 v124, v88, v89
	v_cvt_pk_bf16_f32 v125, v90, v91
	v_cvt_pk_bf16_f32 v126, v92, v93
	v_cvt_pk_bf16_f32 v127, v94, v95
	v_add_f32_e32 v83, v99, v83
	v_add_f32_e32 v243, v243, v83
	s_waitcnt lgkmcnt(9)
	v_mfma_f32_32x32x16_bf16 v[64:79], v[226:229], v[156:159], v[64:79]
	ds_read_b128 v[222:225], v209 offset:18016
	v_add_f32_e32 v84, v100, v84
	v_add_f32_e32 v240, v240, v84
	v_add_f32_e32 v85, v101, v85
	v_add_f32_e32 v241, v241, v85
	v_add_f32_e32 v86, v102, v86
	v_add_f32_e32 v238, v238, v86
	s_waitcnt lgkmcnt(7)
	v_mfma_f32_32x32x16_bf16 v[64:79], v[128:131], v[160:163], v[64:79]
	ds_read_b128 v[226:229], v187 offset:29280
	v_add_f32_e32 v87, v103, v87
	v_add_f32_e32 v239, v239, v87
	v_add_f32_e32 v88, v104, v88
	v_add_f32_e32 v236, v236, v88
	v_add_f32_e32 v89, v105, v89
	v_add_f32_e32 v237, v237, v89
	s_waitcnt lgkmcnt(7)
	v_mfma_f32_32x32x16_bf16 v[16:31], v[132:135], v[120:123], v[16:31]
	ds_read_b128 v[128:131], v187 offset:29312
	v_add_f32_e32 v90, v106, v90
	v_add_f32_e32 v234, v234, v90
	v_add_f32_e32 v91, v107, v91
	v_add_f32_e32 v235, v235, v91
	v_add_f32_e32 v92, v108, v92
	v_add_f32_e32 v232, v232, v92
	s_waitcnt lgkmcnt(7)
	v_mfma_f32_32x32x16_bf16 v[32:47], v[136:139], v[120:123], v[32:47]
	ds_read_b128 v[132:135], v187 offset:29344
	v_add_f32_e32 v93, v109, v93
	v_add_f32_e32 v233, v233, v93
	v_add_f32_e32 v94, v110, v94
	v_add_f32_e32 v230, v230, v94
	s_waitcnt lgkmcnt(7)
	v_mfma_f32_32x32x16_bf16 v[48:63], v[140:143], v[164:167], v[0:15]
	ds_read_b128 v[136:139], v209 offset:35840
	v_exp_f32_e32 v64, v64
	v_exp_f32_e32 v65, v65
	v_exp_f32_e32 v66, v66
	s_waitcnt lgkmcnt(7)
	v_mfma_f32_32x32x16_bf16 v[48:63], v[188:191], v[144:147], v[48:63]
	ds_read_b128 v[140:143], v209 offset:40448
	v_exp_f32_e32 v67, v67
	v_exp_f32_e32 v68, v68
	v_exp_f32_e32 v69, v69
	s_waitcnt lgkmcnt(7)
	v_mfma_f32_32x32x16_bf16 v[48:63], v[168:171], v[148:151], v[48:63]
	ds_read_b128 v[188:191], v209 offset:35872
	v_exp_f32_e32 v70, v70
	v_exp_f32_e32 v71, v71
	v_cvt_pk_bf16_f32 v112, v64, v65
	v_cvt_pk_bf16_f32 v113, v66, v67
	s_waitcnt lgkmcnt(7)
	v_mfma_f32_32x32x16_bf16 v[16:31], v[218:221], v[124:127], v[16:31]
	ds_read_b128 v[168:171], v209 offset:40480
	v_cvt_pk_bf16_f32 v114, v68, v69
	v_cvt_pk_bf16_f32 v115, v70, v71
	v_exp_f32_e32 v72, v72
	v_exp_f32_e32 v73, v73
	s_waitcnt lgkmcnt(7)
	v_mfma_f32_32x32x16_bf16 v[32:47], v[222:225], v[124:127], v[32:47]
	v_exp_f32_e32 v74, v74
	v_exp_f32_e32 v75, v75
	v_exp_f32_e32 v76, v76
	s_waitcnt lgkmcnt(6)
	v_mfma_f32_32x32x16_bf16 v[48:63], v[226:229], v[152:155], v[48:63]
	v_exp_f32_e32 v77, v77
	v_exp_f32_e32 v78, v78
	v_exp_f32_e32 v79, v79
	s_waitcnt lgkmcnt(5)
	v_mfma_f32_32x32x16_bf16 v[48:63], v[128:131], v[156:159], v[48:63]
	v_cvt_pk_bf16_f32 v116, v72, v73
	v_cvt_pk_bf16_f32 v117, v74, v75
	v_cvt_pk_bf16_f32 v118, v76, v77
	v_cvt_pk_bf16_f32 v119, v78, v79
	s_waitcnt lgkmcnt(4)
	v_mfma_f32_32x32x16_bf16 v[48:63], v[132:135], v[160:163], v[48:63]
	v_add_f32_e32 v95, v111, v95
	v_add_f32_e32 v231, v231, v95
	s_waitcnt lgkmcnt(4)
	s_barrier
	ds_read_b128 v[218:221], v187 offset:45056
	ds_read_b128 v[222:225], v187 offset:45088
	ds_read_b128 v[226:229], v187 offset:45120
	ds_read_b128 v[128:131], v187 offset:45152
	s_waitcnt lgkmcnt(7)
	v_mfma_f32_32x32x16_bf16 v[16:31], v[136:139], v[112:115], v[16:31]
	ds_read_b128 v[132:135], v187 offset:45184
	s_waitcnt vmcnt(0)
	ds_write_b128 v211, v[176:179] offset:0
	s_and_saveexec_b64 s[42:43], s[36:37]
	s_cbranch_execz .Lattn_fx_w20
	ds_write_b128 v186, v[172:175] offset:0
.Lattn_fx_w20:
	s_or_b64 exec, exec, s[42:43]
	ds_write_b128 v208, v[180:183] offset:13312
	v_exp_f32_e32 v48, v48
	v_exp_f32_e32 v49, v49
	v_exp_f32_e32 v50, v50
	s_waitcnt lgkmcnt(9)
	v_mfma_f32_32x32x16_bf16 v[32:47], v[140:143], v[112:115], v[32:47]
	ds_read_b128 v[136:139], v187 offset:45216
	global_load_dwordx4 v[176:179], v212, s[6:7]
	s_and_saveexec_b64 s[42:43], s[36:37]
	s_cbranch_execz .Lattn_fx_g21
	global_load_dwordx4 v[172:175], v214, s[6:7]
.Lattn_fx_g21:
	s_or_b64 exec, exec, s[42:43]
	global_load_dwordx4 v[180:183], v204, s[40:41]
	s_add_u32 s6, s6, 0x18000
	s_addc_u32 s7, s7, 0
	s_add_u32 s40, s40, 0x80
	s_addc_u32 s41, s41, 0
	v_exp_f32_e32 v51, v51
	v_exp_f32_e32 v52, v52
	v_exp_f32_e32 v53, v53
	s_waitcnt lgkmcnt(9)
	v_mfma_f32_32x32x16_bf16 v[16:31], v[188:191], v[116:119], v[16:31]
	ds_read_b128 v[140:143], v209 offset:35904
	v_exp_f32_e32 v54, v54
	v_exp_f32_e32 v55, v55
	v_cvt_pk_bf16_f32 v120, v48, v49
	v_cvt_pk_bf16_f32 v121, v50, v51
	s_waitcnt lgkmcnt(9)
	v_mfma_f32_32x32x16_bf16 v[32:47], v[168:171], v[116:119], v[32:47]
	ds_read_b128 v[188:191], v209 offset:40512
	v_cvt_pk_bf16_f32 v122, v52, v53
	v_cvt_pk_bf16_f32 v123, v54, v55
	v_exp_f32_e32 v56, v56
	v_exp_f32_e32 v57, v57
	s_waitcnt lgkmcnt(9)
	v_mfma_f32_32x32x16_bf16 v[96:111], v[218:221], v[164:167], v[0:15]
	ds_read_b128 v[168:171], v187 offset:51712
	v_exp_f32_e32 v58, v58
	v_exp_f32_e32 v59, v59
	v_add_f32_e32 v48, v64, v48
	v_add_f32_e32 v244, v244, v48
	s_waitcnt lgkmcnt(9)
	v_mfma_f32_32x32x16_bf16 v[96:111], v[222:225], v[144:147], v[96:111]
	ds_read_b128 v[218:221], v187 offset:51744
	v_exp_f32_e32 v60, v60
	v_exp_f32_e32 v61, v61
	v_add_f32_e32 v49, v65, v49
	v_add_f32_e32 v245, v245, v49
	s_waitcnt lgkmcnt(9)
	v_mfma_f32_32x32x16_bf16 v[96:111], v[226:229], v[148:151], v[96:111]
	ds_read_b128 v[222:225], v187 offset:51776
	v_exp_f32_e32 v62, v62
	v_exp_f32_e32 v63, v63
	v_add_f32_e32 v50, v66, v50
	v_add_f32_e32 v242, v242, v50
	s_waitcnt lgkmcnt(9)
	v_mfma_f32_32x32x16_bf16 v[96:111], v[128:131], v[152:155], v[96:111]
	ds_read_b128 v[226:229], v209 offset:35936
	v_cvt_pk_bf16_f32 v124, v56, v57
	v_cvt_pk_bf16_f32 v125, v58, v59
	v_cvt_pk_bf16_f32 v126, v60, v61
	v_cvt_pk_bf16_f32 v127, v62, v63
	v_add_f32_e32 v51, v67, v51
	v_add_f32_e32 v243, v243, v51
	s_waitcnt lgkmcnt(9)
	v_mfma_f32_32x32x16_bf16 v[96:111], v[132:135], v[156:159], v[96:111]
	ds_read_b128 v[128:131], v209 offset:40544
	v_add_f32_e32 v52, v68, v52
	v_add_f32_e32 v240, v240, v52
	v_add_f32_e32 v53, v69, v53
	v_add_f32_e32 v241, v241, v53
	v_add_f32_e32 v54, v70, v54
	v_add_f32_e32 v238, v238, v54
	s_waitcnt lgkmcnt(7)
	v_mfma_f32_32x32x16_bf16 v[96:111], v[136:139], v[160:163], v[96:111]
	ds_read_b128 v[132:135], v187 offset:51808
	v_add_f32_e32 v55, v71, v55
	v_add_f32_e32 v239, v239, v55
	v_add_f32_e32 v56, v72, v56
	v_add_f32_e32 v236, v236, v56
	v_add_f32_e32 v57, v73, v57
	v_add_f32_e32 v237, v237, v57
	s_waitcnt lgkmcnt(7)
	v_mfma_f32_32x32x16_bf16 v[16:31], v[140:143], v[120:123], v[16:31]
	ds_read_b128 v[136:139], v187 offset:51840
	v_add_f32_e32 v58, v74, v58
	v_add_f32_e32 v234, v234, v58
	v_add_f32_e32 v59, v75, v59
	v_add_f32_e32 v235, v235, v59
	v_add_f32_e32 v60, v76, v60
	v_add_f32_e32 v232, v232, v60
	s_waitcnt lgkmcnt(7)
	v_mfma_f32_32x32x16_bf16 v[32:47], v[188:191], v[120:123], v[32:47]
	ds_read_b128 v[140:143], v187 offset:51872
	v_add_f32_e32 v61, v77, v61
	v_add_f32_e32 v233, v233, v61
	v_add_f32_e32 v62, v78, v62
	v_add_f32_e32 v230, v230, v62
	s_waitcnt lgkmcnt(7)
	v_mfma_f32_32x32x16_bf16 v[80:95], v[168:171], v[164:167], v[0:15]
	ds_read_b128 v[188:191], v209 offset:58368
	v_exp_f32_e32 v96, v96
	v_exp_f32_e32 v97, v97
	v_exp_f32_e32 v98, v98
	s_waitcnt lgkmcnt(7)
	v_mfma_f32_32x32x16_bf16 v[80:95], v[218:221], v[144:147], v[80:95]
	ds_read_b128 v[168:171], v209 offset:62976
	v_exp_f32_e32 v99, v99
	v_exp_f32_e32 v100, v100
	v_exp_f32_e32 v101, v101
	s_waitcnt lgkmcnt(7)
	v_mfma_f32_32x32x16_bf16 v[80:95], v[222:225], v[148:151], v[80:95]
	ds_read_b128 v[218:221], v209 offset:58400
	v_exp_f32_e32 v102, v102
	v_exp_f32_e32 v103, v103
	v_cvt_pk_bf16_f32 v112, v96, v97
	v_cvt_pk_bf16_f32 v113, v98, v99
	s_waitcnt lgkmcnt(7)
	v_mfma_f32_32x32x16_bf16 v[16:31], v[226:229], v[124:127], v[16:31]
	ds_read_b128 v[222:225], v209 offset:63008
	v_cvt_pk_bf16_f32 v114, v100, v101
	v_cvt_pk_bf16_f32 v115, v102, v103
	v_exp_f32_e32 v104, v104
	v_exp_f32_e32 v105, v105
	s_waitcnt lgkmcnt(7)
	v_mfma_f32_32x32x16_bf16 v[32:47], v[128:131], v[124:127], v[32:47]
	v_exp_f32_e32 v106, v106
	v_exp_f32_e32 v107, v107
	v_exp_f32_e32 v108, v108
	s_waitcnt lgkmcnt(6)
	v_mfma_f32_32x32x16_bf16 v[80:95], v[132:135], v[152:155], v[80:95]
	v_exp_f32_e32 v109, v109
	v_exp_f32_e32 v110, v110
	v_exp_f32_e32 v111, v111
	s_waitcnt lgkmcnt(5)
	v_mfma_f32_32x32x16_bf16 v[80:95], v[136:139], v[156:159], v[80:95]
	v_cvt_pk_bf16_f32 v116, v104, v105
	v_cvt_pk_bf16_f32 v117, v106, v107
	v_cvt_pk_bf16_f32 v118, v108, v109
	v_cvt_pk_bf16_f32 v119, v110, v111
	s_waitcnt lgkmcnt(4)
	v_mfma_f32_32x32x16_bf16 v[80:95], v[140:143], v[160:163], v[80:95]
	v_add_f32_e32 v63, v79, v63
	v_add_f32_e32 v231, v231, v63
	s_waitcnt lgkmcnt(4)
	s_barrier
	ds_read_b128 v[226:229], v187 offset:0
	ds_read_b128 v[128:131], v187 offset:32
	ds_read_b128 v[132:135], v187 offset:64
	ds_read_b128 v[136:139], v187 offset:96
	s_waitcnt lgkmcnt(7)
	v_mfma_f32_32x32x16_bf16 v[16:31], v[188:191], v[112:115], v[16:31]
	ds_read_b128 v[140:143], v187 offset:128
	s_waitcnt vmcnt(0)
	ds_write_b128 v211, v[176:179] offset:22528
	s_and_saveexec_b64 s[42:43], s[36:37]
	s_cbranch_execz .Lattn_fx_w22
	ds_write_b128 v186, v[172:175] offset:22528
.Lattn_fx_w22:
	s_or_b64 exec, exec, s[42:43]
	ds_write_b128 v208, v[180:183] offset:35840
	v_exp_f32_e32 v80, v80
	v_exp_f32_e32 v81, v81
	v_exp_f32_e32 v82, v82
	s_waitcnt lgkmcnt(9)
	v_mfma_f32_32x32x16_bf16 v[32:47], v[168:171], v[112:115], v[32:47]
	ds_read_b128 v[188:191], v187 offset:160
	global_load_dwordx4 v[176:179], v212, s[6:7]
	s_and_saveexec_b64 s[42:43], s[36:37]
	s_cbranch_execz .Lattn_fx_g23
	global_load_dwordx4 v[172:175], v214, s[6:7]
.Lattn_fx_g23:
	s_or_b64 exec, exec, s[42:43]
	global_load_dwordx4 v[180:183], v204, s[40:41]
	s_add_u32 s6, s6, 0x18000
	s_addc_u32 s7, s7, 0
	s_add_u32 s40, s40, 0x80
	s_addc_u32 s41, s41, 0
	v_exp_f32_e32 v83, v83
	v_exp_f32_e32 v84, v84
	v_exp_f32_e32 v85, v85
	s_waitcnt lgkmcnt(9)
	v_mfma_f32_32x32x16_bf16 v[16:31], v[218:221], v[116:119], v[16:31]
	ds_read_b128 v[168:171], v209 offset:58432
	v_exp_f32_e32 v86, v86
	v_exp_f32_e32 v87, v87
	v_cvt_pk_bf16_f32 v120, v80, v81
	v_cvt_pk_bf16_f32 v121, v82, v83
	s_waitcnt lgkmcnt(9)
	v_mfma_f32_32x32x16_bf16 v[32:47], v[222:225], v[116:119], v[32:47]
	ds_read_b128 v[218:221], v209 offset:63040
	v_cvt_pk_bf16_f32 v122, v84, v85
	v_cvt_pk_bf16_f32 v123, v86, v87
	v_exp_f32_e32 v88, v88
	v_exp_f32_e32 v89, v89
	s_waitcnt lgkmcnt(9)
	v_mfma_f32_32x32x16_bf16 v[64:79], v[226:229], v[164:167], v[0:15]
	ds_read_b128 v[222:225], v187 offset:6656
	v_exp_f32_e32 v90, v90
	v_exp_f32_e32 v91, v91
	v_add_f32_e32 v80, v96, v80
	v_add_f32_e32 v244, v244, v80
	s_waitcnt lgkmcnt(9)
	v_mfma_f32_32x32x16_bf16 v[64:79], v[128:131], v[144:147], v[64:79]
	ds_read_b128 v[226:229], v187 offset:6688
	v_exp_f32_e32 v92, v92
	v_exp_f32_e32 v93, v93
	v_add_f32_e32 v81, v97, v81
	v_add_f32_e32 v245, v245, v81
	s_waitcnt lgkmcnt(9)
	v_mfma_f32_32x32x16_bf16 v[64:79], v[132:135], v[148:151], v[64:79]
	ds_read_b128 v[128:131], v187 offset:6720
	v_exp_f32_e32 v94, v94
	v_exp_f32_e32 v95, v95
	v_add_f32_e32 v82, v98, v82
	v_add_f32_e32 v242, v242, v82
	s_waitcnt lgkmcnt(9)
	v_mfma_f32_32x32x16_bf16 v[64:79], v[136:139], v[152:155], v[64:79]
	ds_read_b128 v[132:135], v209 offset:58464
	v_cvt_pk_bf16_f32 v124, v88, v89
	v_cvt_pk_bf16_f32 v125, v90, v91
	v_cvt_pk_bf16_f32 v126, v92, v93
	v_cvt_pk_bf16_f32 v127, v94, v95
	v_add_f32_e32 v83, v99, v83
	v_add_f32_e32 v243, v243, v83
	s_waitcnt lgkmcnt(9)
	v_mfma_f32_32x32x16_bf16 v[64:79], v[140:143], v[156:159], v[64:79]
	ds_read_b128 v[136:139], v209 offset:63072
	v_add_f32_e32 v84, v100, v84
	v_add_f32_e32 v240, v240, v84
	v_add_f32_e32 v85, v101, v85
	v_add_f32_e32 v241, v241, v85
	v_add_f32_e32 v86, v102, v86
	v_add_f32_e32 v238, v238, v86
	s_waitcnt lgkmcnt(7)
	v_mfma_f32_32x32x16_bf16 v[64:79], v[188:191], v[160:163], v[64:79]
	ds_read_b128 v[140:143], v187 offset:6752
	v_add_f32_e32 v87, v103, v87
	v_add_f32_e32 v239, v239, v87
	v_add_f32_e32 v88, v104, v88
	v_add_f32_e32 v236, v236, v88
	v_add_f32_e32 v89, v105, v89
	v_add_f32_e32 v237, v237, v89
	s_waitcnt lgkmcnt(7)
	v_mfma_f32_32x32x16_bf16 v[16:31], v[168:171], v[120:123], v[16:31]
	ds_read_b128 v[188:191], v187 offset:6784
	v_add_f32_e32 v90, v106, v90
	v_add_f32_e32 v234, v234, v90
	v_add_f32_e32 v91, v107, v91
	v_add_f32_e32 v235, v235, v91
	v_add_f32_e32 v92, v108, v92
	v_add_f32_e32 v232, v232, v92
	s_waitcnt lgkmcnt(7)
	v_mfma_f32_32x32x16_bf16 v[32:47], v[218:221], v[120:123], v[32:47]
	ds_read_b128 v[168:171], v187 offset:6816
	v_add_f32_e32 v93, v109, v93
	v_add_f32_e32 v233, v233, v93
	v_add_f32_e32 v94, v110, v94
	v_add_f32_e32 v230, v230, v94
	s_waitcnt lgkmcnt(7)
	v_mfma_f32_32x32x16_bf16 v[48:63], v[222:225], v[164:167], v[0:15]
	ds_read_b128 v[218:221], v209 offset:13312
	v_exp_f32_e32 v64, v64
	v_exp_f32_e32 v65, v65
	v_exp_f32_e32 v66, v66
	s_waitcnt lgkmcnt(7)
	v_mfma_f32_32x32x16_bf16 v[48:63], v[226:229], v[144:147], v[48:63]
	ds_read_b128 v[222:225], v209 offset:17920
	v_exp_f32_e32 v67, v67
	v_exp_f32_e32 v68, v68
	v_exp_f32_e32 v69, v69
	s_waitcnt lgkmcnt(7)
	v_mfma_f32_32x32x16_bf16 v[48:63], v[128:131], v[148:151], v[48:63]
	ds_read_b128 v[226:229], v209 offset:13344
	v_exp_f32_e32 v70, v70
	v_exp_f32_e32 v71, v71
	v_cvt_pk_bf16_f32 v112, v64, v65
	v_cvt_pk_bf16_f32 v113, v66, v67
	s_waitcnt lgkmcnt(7)
	v_mfma_f32_32x32x16_bf16 v[16:31], v[132:135], v[124:127], v[16:31]
	ds_read_b128 v[128:131], v209 offset:17952
	v_cvt_pk_bf16_f32 v114, v68, v69
	v_cvt_pk_bf16_f32 v115, v70, v71
	v_exp_f32_e32 v72, v72
	v_exp_f32_e32 v73, v73
	s_waitcnt lgkmcnt(7)
	v_mfma_f32_32x32x16_bf16 v[32:47], v[136:139], v[124:127], v[32:47]
	v_exp_f32_e32 v74, v74
	v_exp_f32_e32 v75, v75
	v_exp_f32_e32 v76, v76
	s_waitcnt lgkmcnt(6)
	v_mfma_f32_32x32x16_bf16 v[48:63], v[140:143], v[152:155], v[48:63]
	v_exp_f32_e32 v77, v77
	v_exp_f32_e32 v78, v78
	v_exp_f32_e32 v79, v79
	s_waitcnt lgkmcnt(5)
	v_mfma_f32_32x32x16_bf16 v[48:63], v[188:191], v[156:159], v[48:63]
	v_cvt_pk_bf16_f32 v116, v72, v73
	v_cvt_pk_bf16_f32 v117, v74, v75
	v_cvt_pk_bf16_f32 v118, v76, v77
	v_cvt_pk_bf16_f32 v119, v78, v79
	s_waitcnt lgkmcnt(4)
	v_mfma_f32_32x32x16_bf16 v[48:63], v[168:171], v[160:163], v[48:63]
	v_add_f32_e32 v95, v111, v95
	v_add_f32_e32 v231, v231, v95
	s_waitcnt lgkmcnt(4)
	s_barrier
	ds_read_b128 v[132:135], v187 offset:22528
	ds_read_b128 v[136:139], v187 offset:22560
	ds_read_b128 v[140:143], v187 offset:22592
	ds_read_b128 v[188:191], v187 offset:22624
	s_waitcnt lgkmcnt(7)
	v_mfma_f32_32x32x16_bf16 v[16:31], v[218:221], v[112:115], v[16:31]
	ds_read_b128 v[168:171], v187 offset:22656
	s_waitcnt vmcnt(0)
	ds_write_b128 v211, v[176:179] offset:45056
	s_and_saveexec_b64 s[42:43], s[36:37]
	s_cbranch_execz .Lattn_fx_w24
	ds_write_b128 v186, v[172:175] offset:45056
.Lattn_fx_w24:
	s_or_b64 exec, exec, s[42:43]
	ds_write_b128 v208, v[180:183] offset:58368
	v_exp_f32_e32 v48, v48
	v_exp_f32_e32 v49, v49
	v_exp_f32_e32 v50, v50
	s_waitcnt lgkmcnt(9)
	v_mfma_f32_32x32x16_bf16 v[32:47], v[222:225], v[112:115], v[32:47]
	ds_read_b128 v[218:221], v187 offset:22688
	global_load_dwordx4 v[176:179], v212, s[6:7]
	s_and_saveexec_b64 s[42:43], s[36:37]
	s_cbranch_execz .Lattn_fx_g25
	global_load_dwordx4 v[172:175], v214, s[6:7]
.Lattn_fx_g25:
	s_or_b64 exec, exec, s[42:43]
	global_load_dwordx4 v[180:183], v204, s[40:41]
	s_add_u32 s6, s6, 0x18000
	s_addc_u32 s7, s7, 0
	s_add_u32 s40, s40, 0x80
	s_addc_u32 s41, s41, 0
	v_exp_f32_e32 v51, v51
	v_exp_f32_e32 v52, v52
	v_exp_f32_e32 v53, v53
	s_waitcnt lgkmcnt(9)
	v_mfma_f32_32x32x16_bf16 v[16:31], v[226:229], v[116:119], v[16:31]
	ds_read_b128 v[222:225], v209 offset:13376
	v_exp_f32_e32 v54, v54
	v_exp_f32_e32 v55, v55
	v_cvt_pk_bf16_f32 v120, v48, v49
	v_cvt_pk_bf16_f32 v121, v50, v51
	s_waitcnt lgkmcnt(9)
	v_mfma_f32_32x32x16_bf16 v[32:47], v[128:131], v[116:119], v[32:47]
	ds_read_b128 v[226:229], v209 offset:17984
	v_cvt_pk_bf16_f32 v122, v52, v53
	v_cvt_pk_bf16_f32 v123, v54, v55
	v_exp_f32_e32 v56, v56
	v_exp_f32_e32 v57, v57
	s_waitcnt lgkmcnt(9)
	v_mfma_f32_32x32x16_bf16 v[96:111], v[132:135], v[164:167], v[0:15]
	ds_read_b128 v[128:131], v187 offset:29184
	v_exp_f32_e32 v58, v58
	v_exp_f32_e32 v59, v59
	v_add_f32_e32 v48, v64, v48
	v_add_f32_e32 v244, v244, v48
	s_waitcnt lgkmcnt(9)
	v_mfma_f32_32x32x16_bf16 v[96:111], v[136:139], v[144:147], v[96:111]
	ds_read_b128 v[132:135], v187 offset:29216
	v_exp_f32_e32 v60, v60
	v_exp_f32_e32 v61, v61
	v_add_f32_e32 v49, v65, v49
	v_add_f32_e32 v245, v245, v49
	s_waitcnt lgkmcnt(9)
	v_mfma_f32_32x32x16_bf16 v[96:111], v[140:143], v[148:151], v[96:111]
	ds_read_b128 v[136:139], v187 offset:29248
	v_exp_f32_e32 v62, v62
	v_exp_f32_e32 v63, v63
	v_add_f32_e32 v50, v66, v50
	v_add_f32_e32 v242, v242, v50
	s_waitcnt lgkmcnt(9)
	v_mfma_f32_32x32x16_bf16 v[96:111], v[188:191], v[152:155], v[96:111]
	ds_read_b128 v[140:143], v209 offset:13408
	v_cvt_pk_bf16_f32 v124, v56, v57
	v_cvt_pk_bf16_f32 v125, v58, v59
	v_cvt_pk_bf16_f32 v126, v60, v61
	v_cvt_pk_bf16_f32 v127, v62, v63
	v_add_f32_e32 v51, v67, v51
	v_add_f32_e32 v243, v243, v51
	s_waitcnt lgkmcnt(9)
	v_mfma_f32_32x32x16_bf16 v[96:111], v[168:171], v[156:159], v[96:111]
	ds_read_b128 v[188:191], v209 offset:18016
	v_add_f32_e32 v52, v68, v52
	v_add_f32_e32 v240, v240, v52
	v_add_f32_e32 v53, v69, v53
	v_add_f32_e32 v241, v241, v53
	v_add_f32_e32 v54, v70, v54
	v_add_f32_e32 v238, v238, v54
	s_waitcnt lgkmcnt(7)
	v_mfma_f32_32x32x16_bf16 v[96:111], v[218:221], v[160:163], v[96:111]
	ds_read_b128 v[168:171], v187 offset:29280
	v_add_f32_e32 v55, v71, v55
	v_add_f32_e32 v239, v239, v55
	v_add_f32_e32 v56, v72, v56
	v_add_f32_e32 v236, v236, v56
	v_add_f32_e32 v57, v73, v57
	v_add_f32_e32 v237, v237, v57
	s_waitcnt lgkmcnt(7)
	v_mfma_f32_32x32x16_bf16 v[16:31], v[222:225], v[120:123], v[16:31]
	ds_read_b128 v[218:221], v187 offset:29312
	v_add_f32_e32 v58, v74, v58
	v_add_f32_e32 v234, v234, v58
	v_add_f32_e32 v59, v75, v59
	v_add_f32_e32 v235, v235, v59
	v_add_f32_e32 v60, v76, v60
	v_add_f32_e32 v232, v232, v60
	s_waitcnt lgkmcnt(7)
	v_mfma_f32_32x32x16_bf16 v[32:47], v[226:229], v[120:123], v[32:47]
	ds_read_b128 v[222:225], v187 offset:29344
	v_add_f32_e32 v61, v77, v61
	v_add_f32_e32 v233, v233, v61
	v_add_f32_e32 v62, v78, v62
	v_add_f32_e32 v230, v230, v62
	s_waitcnt lgkmcnt(7)
	v_mfma_f32_32x32x16_bf16 v[80:95], v[128:131], v[164:167], v[0:15]
	ds_read_b128 v[226:229], v209 offset:35840
	v_exp_f32_e32 v96, v96
	v_exp_f32_e32 v97, v97
	v_exp_f32_e32 v98, v98
	s_waitcnt lgkmcnt(7)
	v_mfma_f32_32x32x16_bf16 v[80:95], v[132:135], v[144:147], v[80:95]
	ds_read_b128 v[128:131], v209 offset:40448
	v_exp_f32_e32 v99, v99
	v_exp_f32_e32 v100, v100
	v_exp_f32_e32 v101, v101
	s_waitcnt lgkmcnt(7)
	v_mfma_f32_32x32x16_bf16 v[80:95], v[136:139], v[148:151], v[80:95]
	ds_read_b128 v[132:135], v209 offset:35872
	v_exp_f32_e32 v102, v102
	v_exp_f32_e32 v103, v103
	v_cvt_pk_bf16_f32 v112, v96, v97
	v_cvt_pk_bf16_f32 v113, v98, v99
	s_waitcnt lgkmcnt(7)
	v_mfma_f32_32x32x16_bf16 v[16:31], v[140:143], v[124:127], v[16:31]
	ds_read_b128 v[136:139], v209 offset:40480
	v_cvt_pk_bf16_f32 v114, v100, v101
	v_cvt_pk_bf16_f32 v115, v102, v103
	v_exp_f32_e32 v104, v104
	v_exp_f32_e32 v105, v105
	s_waitcnt lgkmcnt(7)
	v_mfma_f32_32x32x16_bf16 v[32:47], v[188:191], v[124:127], v[32:47]
	v_exp_f32_e32 v106, v106
	v_exp_f32_e32 v107, v107
	v_exp_f32_e32 v108, v108
	s_waitcnt lgkmcnt(6)
	v_mfma_f32_32x32x16_bf16 v[80:95], v[168:171], v[152:155], v[80:95]
	v_exp_f32_e32 v109, v109
	v_exp_f32_e32 v110, v110
	v_exp_f32_e32 v111, v111
	s_waitcnt lgkmcnt(5)
	v_mfma_f32_32x32x16_bf16 v[80:95], v[218:221], v[156:159], v[80:95]
	v_cvt_pk_bf16_f32 v116, v104, v105
	v_cvt_pk_bf16_f32 v117, v106, v107
	v_cvt_pk_bf16_f32 v118, v108, v109
	v_cvt_pk_bf16_f32 v119, v110, v111
	s_waitcnt lgkmcnt(4)
	v_mfma_f32_32x32x16_bf16 v[80:95], v[222:225], v[160:163], v[80:95]
	v_add_f32_e32 v63, v79, v63
	v_add_f32_e32 v231, v231, v63
	s_waitcnt lgkmcnt(4)
	s_barrier
	ds_read_b128 v[140:143], v187 offset:45056
	ds_read_b128 v[188:191], v187 offset:45088
	ds_read_b128 v[168:171], v187 offset:45120
	ds_read_b128 v[218:221], v187 offset:45152
	s_waitcnt lgkmcnt(7)
	v_mfma_f32_32x32x16_bf16 v[16:31], v[226:229], v[112:115], v[16:31]
	ds_read_b128 v[222:225], v187 offset:45184
	s_waitcnt vmcnt(0)
	ds_write_b128 v211, v[176:179] offset:0
	s_and_saveexec_b64 s[42:43], s[36:37]
	s_cbranch_execz .Lattn_fx_w26
	ds_write_b128 v186, v[172:175] offset:0
.Lattn_fx_w26:
	s_or_b64 exec, exec, s[42:43]
	ds_write_b128 v208, v[180:183] offset:13312
	v_exp_f32_e32 v80, v80
	v_exp_f32_e32 v81, v81
	v_exp_f32_e32 v82, v82
	s_waitcnt lgkmcnt(9)
	v_mfma_f32_32x32x16_bf16 v[32:47], v[128:131], v[112:115], v[32:47]
	ds_read_b128 v[226:229], v187 offset:45216
	global_load_dwordx4 v[176:179], v212, s[6:7]
	s_and_saveexec_b64 s[42:43], s[36:37]
	s_cbranch_execz .Lattn_fx_g27
	global_load_dwordx4 v[172:175], v214, s[6:7]
.Lattn_fx_g27:
	s_or_b64 exec, exec, s[42:43]
	global_load_dwordx4 v[180:183], v204, s[40:41]
	s_add_u32 s6, s6, 0x18000
	s_addc_u32 s7, s7, 0
	s_add_u32 s40, s40, 0x80
	s_addc_u32 s41, s41, 0
	v_exp_f32_e32 v83, v83
	v_exp_f32_e32 v84, v84
	v_exp_f32_e32 v85, v85
	s_waitcnt lgkmcnt(9)
	v_mfma_f32_32x32x16_bf16 v[16:31], v[132:135], v[116:119], v[16:31]
	ds_read_b128 v[128:131], v209 offset:35904
	v_exp_f32_e32 v86, v86
	v_exp_f32_e32 v87, v87
	v_cvt_pk_bf16_f32 v120, v80, v81
	v_cvt_pk_bf16_f32 v121, v82, v83
	s_waitcnt lgkmcnt(9)
	v_mfma_f32_32x32x16_bf16 v[32:47], v[136:139], v[116:119], v[32:47]
	ds_read_b128 v[132:135], v209 offset:40512
	v_cvt_pk_bf16_f32 v122, v84, v85
	v_cvt_pk_bf16_f32 v123, v86, v87
	v_exp_f32_e32 v88, v88
	v_exp_f32_e32 v89, v89
	s_waitcnt lgkmcnt(9)
	v_mfma_f32_32x32x16_bf16 v[64:79], v[140:143], v[164:167], v[0:15]
	ds_read_b128 v[136:139], v187 offset:51712
	v_exp_f32_e32 v90, v90
	v_exp_f32_e32 v91, v91
	v_add_f32_e32 v80, v96, v80
	v_add_f32_e32 v244, v244, v80
	s_waitcnt lgkmcnt(9)
	v_mfma_f32_32x32x16_bf16 v[64:79], v[188:191], v[144:147], v[64:79]
	ds_read_b128 v[140:143], v187 offset:51744
	v_exp_f32_e32 v92, v92
	v_exp_f32_e32 v93, v93
	v_add_f32_e32 v81, v97, v81
	v_add_f32_e32 v245, v245, v81
	s_waitcnt lgkmcnt(9)
	v_mfma_f32_32x32x16_bf16 v[64:79], v[168:171], v[148:151], v[64:79]
	ds_read_b128 v[188:191], v187 offset:51776
	v_exp_f32_e32 v94, v94
	v_exp_f32_e32 v95, v95
	v_add_f32_e32 v82, v98, v82
	v_add_f32_e32 v242, v242, v82
	s_waitcnt lgkmcnt(9)
	v_mfma_f32_32x32x16_bf16 v[64:79], v[218:221], v[152:155], v[64:79]
	ds_read_b128 v[168:171], v209 offset:35936
	v_cvt_pk_bf16_f32 v124, v88, v89
	v_cvt_pk_bf16_f32 v125, v90, v91
	v_cvt_pk_bf16_f32 v126, v92, v93
	v_cvt_pk_bf16_f32 v127, v94, v95
	v_add_f32_e32 v83, v99, v83
	v_add_f32_e32 v243, v243, v83
	s_waitcnt lgkmcnt(9)
	v_mfma_f32_32x32x16_bf16 v[64:79], v[222:225], v[156:159], v[64:79]
	ds_read_b128 v[218:221], v209 offset:40544
	v_add_f32_e32 v84, v100, v84
	v_add_f32_e32 v240, v240, v84
	v_add_f32_e32 v85, v101, v85
	v_add_f32_e32 v241, v241, v85
	v_add_f32_e32 v86, v102, v86
	v_add_f32_e32 v238, v238, v86
	s_waitcnt lgkmcnt(7)
	v_mfma_f32_32x32x16_bf16 v[64:79], v[226:229], v[160:163], v[64:79]
	ds_read_b128 v[222:225], v187 offset:51808
	v_add_f32_e32 v87, v103, v87
	v_add_f32_e32 v239, v239, v87
	v_add_f32_e32 v88, v104, v88
	v_add_f32_e32 v236, v236, v88
	v_add_f32_e32 v89, v105, v89
	v_add_f32_e32 v237, v237, v89
	s_waitcnt lgkmcnt(7)
	v_mfma_f32_32x32x16_bf16 v[16:31], v[128:131], v[120:123], v[16:31]
	ds_read_b128 v[226:229], v187 offset:51840
	v_add_f32_e32 v90, v106, v90
	v_add_f32_e32 v234, v234, v90
	v_add_f32_e32 v91, v107, v91
	v_add_f32_e32 v235, v235, v91
	v_add_f32_e32 v92, v108, v92
	v_add_f32_e32 v232, v232, v92
	s_waitcnt lgkmcnt(7)
	v_mfma_f32_32x32x16_bf16 v[32:47], v[132:135], v[120:123], v[32:47]
	ds_read_b128 v[128:131], v187 offset:51872
	v_add_f32_e32 v93, v109, v93
	v_add_f32_e32 v233, v233, v93
	v_add_f32_e32 v94, v110, v94
	v_add_f32_e32 v230, v230, v94
	s_waitcnt lgkmcnt(7)
	v_mfma_f32_32x32x16_bf16 v[48:63], v[136:139], v[164:167], v[0:15]
	ds_read_b128 v[132:135], v209 offset:58368
	v_exp_f32_e32 v64, v64
	v_exp_f32_e32 v65, v65
	v_exp_f32_e32 v66, v66
	s_waitcnt lgkmcnt(7)
	v_mfma_f32_32x32x16_bf16 v[48:63], v[140:143], v[144:147], v[48:63]
	ds_read_b128 v[136:139], v209 offset:62976
	v_exp_f32_e32 v67, v67
	v_exp_f32_e32 v68, v68
	v_exp_f32_e32 v69, v69
	s_waitcnt lgkmcnt(7)
	v_mfma_f32_32x32x16_bf16 v[48:63], v[188:191], v[148:151], v[48:63]
	ds_read_b128 v[140:143], v209 offset:58400
	v_exp_f32_e32 v70, v70
	v_exp_f32_e32 v71, v71
	v_cvt_pk_bf16_f32 v112, v64, v65
	v_cvt_pk_bf16_f32 v113, v66, v67
	s_waitcnt lgkmcnt(7)
	v_mfma_f32_32x32x16_bf16 v[16:31], v[168:171], v[124:127], v[16:31]
	ds_read_b128 v[188:191], v209 offset:63008
	v_cvt_pk_bf16_f32 v114, v68, v69
	v_cvt_pk_bf16_f32 v115, v70, v71
	v_exp_f32_e32 v72, v72
	v_exp_f32_e32 v73, v73
	s_waitcnt lgkmcnt(7)
	v_mfma_f32_32x32x16_bf16 v[32:47], v[218:221], v[124:127], v[32:47]
	v_exp_f32_e32 v74, v74
	v_exp_f32_e32 v75, v75
	v_exp_f32_e32 v76, v76
	s_waitcnt lgkmcnt(6)
	v_mfma_f32_32x32x16_bf16 v[48:63], v[222:225], v[152:155], v[48:63]
	v_exp_f32_e32 v77, v77
	v_exp_f32_e32 v78, v78
	v_exp_f32_e32 v79, v79
	s_waitcnt lgkmcnt(5)
	v_mfma_f32_32x32x16_bf16 v[48:63], v[226:229], v[156:159], v[48:63]
	v_cvt_pk_bf16_f32 v116, v72, v73
	v_cvt_pk_bf16_f32 v117, v74, v75
	v_cvt_pk_bf16_f32 v118, v76, v77
	v_cvt_pk_bf16_f32 v119, v78, v79
	s_waitcnt lgkmcnt(4)
	v_mfma_f32_32x32x16_bf16 v[48:63], v[128:131], v[160:163], v[48:63]
	v_add_f32_e32 v95, v111, v95
	v_add_f32_e32 v231, v231, v95
	s_waitcnt lgkmcnt(4)
	s_barrier
	ds_read_b128 v[168:171], v187 offset:0
	ds_read_b128 v[218:221], v187 offset:32
	ds_read_b128 v[222:225], v187 offset:64
	ds_read_b128 v[226:229], v187 offset:96
	s_waitcnt lgkmcnt(7)
	v_mfma_f32_32x32x16_bf16 v[16:31], v[132:135], v[112:115], v[16:31]
	ds_read_b128 v[128:131], v187 offset:128
	s_waitcnt vmcnt(0)
	ds_write_b128 v211, v[176:179] offset:22528
	s_and_saveexec_b64 s[42:43], s[36:37]
	s_cbranch_execz .Lattn_fx_w28
	ds_write_b128 v186, v[172:175] offset:22528
.Lattn_fx_w28:
	s_or_b64 exec, exec, s[42:43]
	ds_write_b128 v208, v[180:183] offset:35840
	v_exp_f32_e32 v48, v48
	v_exp_f32_e32 v49, v49
	v_exp_f32_e32 v50, v50
	s_waitcnt lgkmcnt(9)
	v_mfma_f32_32x32x16_bf16 v[32:47], v[136:139], v[112:115], v[32:47]
	ds_read_b128 v[132:135], v187 offset:160
	global_load_dwordx4 v[176:179], v212, s[6:7]
	s_and_saveexec_b64 s[42:43], s[36:37]
	s_cbranch_execz .Lattn_fx_g29
	global_load_dwordx4 v[172:175], v214, s[6:7]
.Lattn_fx_g29:
	s_or_b64 exec, exec, s[42:43]
	global_load_dwordx4 v[180:183], v204, s[40:41]
	s_add_u32 s6, s6, 0x18000
	s_addc_u32 s7, s7, 0
	s_add_u32 s40, s40, 0x80
	s_addc_u32 s41, s41, 0
	v_exp_f32_e32 v51, v51
	v_exp_f32_e32 v52, v52
	v_exp_f32_e32 v53, v53
	s_waitcnt lgkmcnt(9)
	v_mfma_f32_32x32x16_bf16 v[16:31], v[140:143], v[116:119], v[16:31]
	ds_read_b128 v[136:139], v209 offset:58432
	v_exp_f32_e32 v54, v54
	v_exp_f32_e32 v55, v55
	v_cvt_pk_bf16_f32 v120, v48, v49
	v_cvt_pk_bf16_f32 v121, v50, v51
	s_waitcnt lgkmcnt(9)
	v_mfma_f32_32x32x16_bf16 v[32:47], v[188:191], v[116:119], v[32:47]
	ds_read_b128 v[140:143], v209 offset:63040
	v_cvt_pk_bf16_f32 v122, v52, v53
	v_cvt_pk_bf16_f32 v123, v54, v55
	v_exp_f32_e32 v56, v56
	v_exp_f32_e32 v57, v57
	s_waitcnt lgkmcnt(9)
	v_mfma_f32_32x32x16_bf16 v[96:111], v[168:171], v[164:167], v[0:15]
	ds_read_b128 v[188:191], v187 offset:6656
	v_exp_f32_e32 v58, v58
	v_exp_f32_e32 v59, v59
	v_add_f32_e32 v48, v64, v48
	v_add_f32_e32 v244, v244, v48
	s_waitcnt lgkmcnt(9)
	v_mfma_f32_32x32x16_bf16 v[96:111], v[218:221], v[144:147], v[96:111]
	ds_read_b128 v[168:171], v187 offset:6688
	v_exp_f32_e32 v60, v60
	v_exp_f32_e32 v61, v61
	v_add_f32_e32 v49, v65, v49
	v_add_f32_e32 v245, v245, v49
	s_waitcnt lgkmcnt(9)
	v_mfma_f32_32x32x16_bf16 v[96:111], v[222:225], v[148:151], v[96:111]
	ds_read_b128 v[218:221], v187 offset:6720
	v_exp_f32_e32 v62, v62
	v_exp_f32_e32 v63, v63
	v_add_f32_e32 v50, v66, v50
	v_add_f32_e32 v242, v242, v50
	s_waitcnt lgkmcnt(9)
	v_mfma_f32_32x32x16_bf16 v[96:111], v[226:229], v[152:155], v[96:111]
	ds_read_b128 v[222:225], v209 offset:58464
	v_cvt_pk_bf16_f32 v124, v56, v57
	v_cvt_pk_bf16_f32 v125, v58, v59
	v_cvt_pk_bf16_f32 v126, v60, v61
	v_cvt_pk_bf16_f32 v127, v62, v63
	v_add_f32_e32 v51, v67, v51
	v_add_f32_e32 v243, v243, v51
	s_waitcnt lgkmcnt(9)
	v_mfma_f32_32x32x16_bf16 v[96:111], v[128:131], v[156:159], v[96:111]
	ds_read_b128 v[226:229], v209 offset:63072
	v_add_f32_e32 v52, v68, v52
	v_add_f32_e32 v240, v240, v52
	v_add_f32_e32 v53, v69, v53
	v_add_f32_e32 v241, v241, v53
	v_add_f32_e32 v54, v70, v54
	v_add_f32_e32 v238, v238, v54
	s_waitcnt lgkmcnt(7)
	v_mfma_f32_32x32x16_bf16 v[96:111], v[132:135], v[160:163], v[96:111]
	ds_read_b128 v[128:131], v187 offset:6752
	v_add_f32_e32 v55, v71, v55
	v_add_f32_e32 v239, v239, v55
	v_add_f32_e32 v56, v72, v56
	v_add_f32_e32 v236, v236, v56
	v_add_f32_e32 v57, v73, v57
	v_add_f32_e32 v237, v237, v57
	s_waitcnt lgkmcnt(7)
	v_mfma_f32_32x32x16_bf16 v[16:31], v[136:139], v[120:123], v[16:31]
	ds_read_b128 v[132:135], v187 offset:6784
	v_add_f32_e32 v58, v74, v58
	v_add_f32_e32 v234, v234, v58
	v_add_f32_e32 v59, v75, v59
	v_add_f32_e32 v235, v235, v59
	v_add_f32_e32 v60, v76, v60
	v_add_f32_e32 v232, v232, v60
	s_waitcnt lgkmcnt(7)
	v_mfma_f32_32x32x16_bf16 v[32:47], v[140:143], v[120:123], v[32:47]
	ds_read_b128 v[136:139], v187 offset:6816
	v_add_f32_e32 v61, v77, v61
	v_add_f32_e32 v233, v233, v61
	v_add_f32_e32 v62, v78, v62
	v_add_f32_e32 v230, v230, v62
	s_waitcnt lgkmcnt(7)
	v_mfma_f32_32x32x16_bf16 v[80:95], v[188:191], v[164:167], v[0:15]
	ds_read_b128 v[140:143], v209 offset:13312
	v_exp_f32_e32 v96, v96
	v_exp_f32_e32 v97, v97
	v_exp_f32_e32 v98, v98
	s_waitcnt lgkmcnt(7)
	v_mfma_f32_32x32x16_bf16 v[80:95], v[168:171], v[144:147], v[80:95]
	ds_read_b128 v[188:191], v209 offset:17920
	v_exp_f32_e32 v99, v99
	v_exp_f32_e32 v100, v100
	v_exp_f32_e32 v101, v101
	s_waitcnt lgkmcnt(7)
	v_mfma_f32_32x32x16_bf16 v[80:95], v[218:221], v[148:151], v[80:95]
	ds_read_b128 v[168:171], v209 offset:13344
	v_exp_f32_e32 v102, v102
	v_exp_f32_e32 v103, v103
	v_cvt_pk_bf16_f32 v112, v96, v97
	v_cvt_pk_bf16_f32 v113, v98, v99
	s_waitcnt lgkmcnt(7)
	v_mfma_f32_32x32x16_bf16 v[16:31], v[222:225], v[124:127], v[16:31]
	ds_read_b128 v[218:221], v209 offset:17952
	v_cvt_pk_bf16_f32 v114, v100, v101
	v_cvt_pk_bf16_f32 v115, v102, v103
	v_exp_f32_e32 v104, v104
	v_exp_f32_e32 v105, v105
	s_waitcnt lgkmcnt(7)
	v_mfma_f32_32x32x16_bf16 v[32:47], v[226:229], v[124:127], v[32:47]
	v_exp_f32_e32 v106, v106
	v_exp_f32_e32 v107, v107
	v_exp_f32_e32 v108, v108
	s_waitcnt lgkmcnt(6)
	v_mfma_f32_32x32x16_bf16 v[80:95], v[128:131], v[152:155], v[80:95]
	v_exp_f32_e32 v109, v109
	v_exp_f32_e32 v110, v110
	v_exp_f32_e32 v111, v111
	s_waitcnt lgkmcnt(5)
	v_mfma_f32_32x32x16_bf16 v[80:95], v[132:135], v[156:159], v[80:95]
	v_cvt_pk_bf16_f32 v116, v104, v105
	v_cvt_pk_bf16_f32 v117, v106, v107
	v_cvt_pk_bf16_f32 v118, v108, v109
	v_cvt_pk_bf16_f32 v119, v110, v111
	s_waitcnt lgkmcnt(4)
	v_mfma_f32_32x32x16_bf16 v[80:95], v[136:139], v[160:163], v[80:95]
	v_add_f32_e32 v63, v79, v63
	v_add_f32_e32 v231, v231, v63
	s_waitcnt lgkmcnt(4)
	s_barrier
	ds_read_b128 v[222:225], v187 offset:22528
	ds_read_b128 v[226:229], v187 offset:22560
	ds_read_b128 v[128:131], v187 offset:22592
	ds_read_b128 v[132:135], v187 offset:22624
	s_waitcnt lgkmcnt(7)
	v_mfma_f32_32x32x16_bf16 v[16:31], v[140:143], v[112:115], v[16:31]
	ds_read_b128 v[136:139], v187 offset:22656
	s_waitcnt vmcnt(0)
	ds_write_b128 v211, v[176:179] offset:45056
	s_and_saveexec_b64 s[42:43], s[36:37]
	s_cbranch_execz .Lattn_fx_w30
	ds_write_b128 v186, v[172:175] offset:45056
.Lattn_fx_w30:
	s_or_b64 exec, exec, s[42:43]
	ds_write_b128 v208, v[180:183] offset:58368
	v_exp_f32_e32 v80, v80
	v_exp_f32_e32 v81, v81
	v_exp_f32_e32 v82, v82
	s_waitcnt lgkmcnt(9)
	v_mfma_f32_32x32x16_bf16 v[32:47], v[188:191], v[112:115], v[32:47]
	ds_read_b128 v[140:143], v187 offset:22688
	global_load_dwordx4 v[176:179], v212, s[6:7]
	s_and_saveexec_b64 s[42:43], s[36:37]
	s_cbranch_execz .Lattn_fx_g31
	global_load_dwordx4 v[172:175], v214, s[6:7]
.Lattn_fx_g31:
	s_or_b64 exec, exec, s[42:43]
	global_load_dwordx4 v[180:183], v204, s[40:41]
	s_add_u32 s6, s6, 0x18000
	s_addc_u32 s7, s7, 0
	s_add_u32 s40, s40, 0x80
	s_addc_u32 s41, s41, 0
	v_exp_f32_e32 v83, v83
	v_exp_f32_e32 v84, v84
	v_exp_f32_e32 v85, v85
	s_waitcnt lgkmcnt(9)
	v_mfma_f32_32x32x16_bf16 v[16:31], v[168:171], v[116:119], v[16:31]
	ds_read_b128 v[188:191], v209 offset:13376
	v_exp_f32_e32 v86, v86
	v_exp_f32_e32 v87, v87
	v_cvt_pk_bf16_f32 v120, v80, v81
	v_cvt_pk_bf16_f32 v121, v82, v83
	s_waitcnt lgkmcnt(9)
	v_mfma_f32_32x32x16_bf16 v[32:47], v[218:221], v[116:119], v[32:47]
	ds_read_b128 v[168:171], v209 offset:17984
	v_cvt_pk_bf16_f32 v122, v84, v85
	v_cvt_pk_bf16_f32 v123, v86, v87
	v_exp_f32_e32 v88, v88
	v_exp_f32_e32 v89, v89
	s_waitcnt lgkmcnt(9)
	v_mfma_f32_32x32x16_bf16 v[64:79], v[222:225], v[164:167], v[0:15]
	ds_read_b128 v[218:221], v187 offset:29184
	v_exp_f32_e32 v90, v90
	v_exp_f32_e32 v91, v91
	v_add_f32_e32 v80, v96, v80
	v_add_f32_e32 v244, v244, v80
	s_waitcnt lgkmcnt(9)
	v_mfma_f32_32x32x16_bf16 v[64:79], v[226:229], v[144:147], v[64:79]
	ds_read_b128 v[222:225], v187 offset:29216
	v_exp_f32_e32 v92, v92
	v_exp_f32_e32 v93, v93
	v_add_f32_e32 v81, v97, v81
	v_add_f32_e32 v245, v245, v81
	s_waitcnt lgkmcnt(9)
	v_mfma_f32_32x32x16_bf16 v[64:79], v[128:131], v[148:151], v[64:79]
	ds_read_b128 v[226:229], v187 offset:29248
	v_exp_f32_e32 v94, v94
	v_exp_f32_e32 v95, v95
	v_add_f32_e32 v82, v98, v82
	v_add_f32_e32 v242, v242, v82
	s_waitcnt lgkmcnt(9)
	v_mfma_f32_32x32x16_bf16 v[64:79], v[132:135], v[152:155], v[64:79]
	ds_read_b128 v[128:131], v209 offset:13408
	v_cvt_pk_bf16_f32 v124, v88, v89
	v_cvt_pk_bf16_f32 v125, v90, v91
	v_cvt_pk_bf16_f32 v126, v92, v93
	v_cvt_pk_bf16_f32 v127, v94, v95
	v_add_f32_e32 v83, v99, v83
	v_add_f32_e32 v243, v243, v83
	s_waitcnt lgkmcnt(9)
	v_mfma_f32_32x32x16_bf16 v[64:79], v[136:139], v[156:159], v[64:79]
	ds_read_b128 v[132:135], v209 offset:18016
	v_add_f32_e32 v84, v100, v84
	v_add_f32_e32 v240, v240, v84
	v_add_f32_e32 v85, v101, v85
	v_add_f32_e32 v241, v241, v85
	v_add_f32_e32 v86, v102, v86
	v_add_f32_e32 v238, v238, v86
	s_waitcnt lgkmcnt(7)
	v_mfma_f32_32x32x16_bf16 v[64:79], v[140:143], v[160:163], v[64:79]
	ds_read_b128 v[136:139], v187 offset:29280
	v_add_f32_e32 v87, v103, v87
	v_add_f32_e32 v239, v239, v87
	v_add_f32_e32 v88, v104, v88
	v_add_f32_e32 v236, v236, v88
	v_add_f32_e32 v89, v105, v89
	v_add_f32_e32 v237, v237, v89
	s_waitcnt lgkmcnt(7)
	v_mfma_f32_32x32x16_bf16 v[16:31], v[188:191], v[120:123], v[16:31]
	ds_read_b128 v[140:143], v187 offset:29312
	v_add_f32_e32 v90, v106, v90
	v_add_f32_e32 v234, v234, v90
	v_add_f32_e32 v91, v107, v91
	v_add_f32_e32 v235, v235, v91
	v_add_f32_e32 v92, v108, v92
	v_add_f32_e32 v232, v232, v92
	s_waitcnt lgkmcnt(7)
	v_mfma_f32_32x32x16_bf16 v[32:47], v[168:171], v[120:123], v[32:47]
	ds_read_b128 v[188:191], v187 offset:29344
	v_add_f32_e32 v93, v109, v93
	v_add_f32_e32 v233, v233, v93
	v_add_f32_e32 v94, v110, v94
	v_add_f32_e32 v230, v230, v94
	s_waitcnt lgkmcnt(7)
	v_mfma_f32_32x32x16_bf16 v[48:63], v[218:221], v[164:167], v[0:15]
	ds_read_b128 v[168:171], v209 offset:35840
	v_exp_f32_e32 v64, v64
	v_exp_f32_e32 v65, v65
	v_exp_f32_e32 v66, v66
	s_waitcnt lgkmcnt(7)
	v_mfma_f32_32x32x16_bf16 v[48:63], v[222:225], v[144:147], v[48:63]
	ds_read_b128 v[218:221], v209 offset:40448
	v_exp_f32_e32 v67, v67
	v_exp_f32_e32 v68, v68
	v_exp_f32_e32 v69, v69
	s_waitcnt lgkmcnt(7)
	v_mfma_f32_32x32x16_bf16 v[48:63], v[226:229], v[148:151], v[48:63]
	ds_read_b128 v[222:225], v209 offset:35872
	v_exp_f32_e32 v70, v70
	v_exp_f32_e32 v71, v71
	v_cvt_pk_bf16_f32 v112, v64, v65
	v_cvt_pk_bf16_f32 v113, v66, v67
	s_waitcnt lgkmcnt(7)
	v_mfma_f32_32x32x16_bf16 v[16:31], v[128:131], v[124:127], v[16:31]
	ds_read_b128 v[226:229], v209 offset:40480
	v_cvt_pk_bf16_f32 v114, v68, v69
	v_cvt_pk_bf16_f32 v115, v70, v71
	v_exp_f32_e32 v72, v72
	v_exp_f32_e32 v73, v73
	s_waitcnt lgkmcnt(7)
	v_mfma_f32_32x32x16_bf16 v[32:47], v[132:135], v[124:127], v[32:47]
	v_exp_f32_e32 v74, v74
	v_exp_f32_e32 v75, v75
	v_exp_f32_e32 v76, v76
	s_waitcnt lgkmcnt(6)
	v_mfma_f32_32x32x16_bf16 v[48:63], v[136:139], v[152:155], v[48:63]
	v_exp_f32_e32 v77, v77
	v_exp_f32_e32 v78, v78
	v_exp_f32_e32 v79, v79
	s_waitcnt lgkmcnt(5)
	v_mfma_f32_32x32x16_bf16 v[48:63], v[140:143], v[156:159], v[48:63]
	v_cvt_pk_bf16_f32 v116, v72, v73
	v_cvt_pk_bf16_f32 v117, v74, v75
	v_cvt_pk_bf16_f32 v118, v76, v77
	v_cvt_pk_bf16_f32 v119, v78, v79
	s_waitcnt lgkmcnt(4)
	v_mfma_f32_32x32x16_bf16 v[48:63], v[188:191], v[160:163], v[48:63]
	v_add_f32_e32 v95, v111, v95
	v_add_f32_e32 v231, v231, v95
	s_waitcnt lgkmcnt(4)
	s_barrier
	ds_read_b128 v[128:131], v187 offset:45056
	ds_read_b128 v[132:135], v187 offset:45088
	ds_read_b128 v[136:139], v187 offset:45120
	ds_read_b128 v[140:143], v187 offset:45152
	s_waitcnt lgkmcnt(7)
	v_mfma_f32_32x32x16_bf16 v[16:31], v[168:171], v[112:115], v[16:31]
	ds_read_b128 v[188:191], v187 offset:45184
	s_waitcnt vmcnt(0)
	ds_write_b128 v211, v[176:179] offset:0
	s_and_saveexec_b64 s[42:43], s[36:37]
	s_cbranch_execz .Lattn_fx_w32
	ds_write_b128 v186, v[172:175] offset:0
.Lattn_fx_w32:
	s_or_b64 exec, exec, s[42:43]
	ds_write_b128 v208, v[180:183] offset:13312
	v_exp_f32_e32 v48, v48
	v_exp_f32_e32 v49, v49
	v_exp_f32_e32 v50, v50
	s_waitcnt lgkmcnt(9)
	v_mfma_f32_32x32x16_bf16 v[32:47], v[218:221], v[112:115], v[32:47]
	ds_read_b128 v[168:171], v187 offset:45216
	global_load_dwordx4 v[176:179], v212, s[6:7]
	s_and_saveexec_b64 s[42:43], s[36:37]
	s_cbranch_execz .Lattn_fx_g33
	global_load_dwordx4 v[172:175], v214, s[6:7]
.Lattn_fx_g33:
	s_or_b64 exec, exec, s[42:43]
	global_load_dwordx4 v[180:183], v204, s[40:41]
	s_add_u32 s6, s6, 0x18000
	s_addc_u32 s7, s7, 0
	s_add_u32 s40, s40, 0x80
	s_addc_u32 s41, s41, 0
	v_exp_f32_e32 v51, v51
	v_exp_f32_e32 v52, v52
	v_exp_f32_e32 v53, v53
	s_waitcnt lgkmcnt(9)
	v_mfma_f32_32x32x16_bf16 v[16:31], v[222:225], v[116:119], v[16:31]
	ds_read_b128 v[218:221], v209 offset:35904
	v_exp_f32_e32 v54, v54
	v_exp_f32_e32 v55, v55
	v_cvt_pk_bf16_f32 v120, v48, v49
	v_cvt_pk_bf16_f32 v121, v50, v51
	s_waitcnt lgkmcnt(9)
	v_mfma_f32_32x32x16_bf16 v[32:47], v[226:229], v[116:119], v[32:47]
	ds_read_b128 v[222:225], v209 offset:40512
	v_cvt_pk_bf16_f32 v122, v52, v53
	v_cvt_pk_bf16_f32 v123, v54, v55
	v_exp_f32_e32 v56, v56
	v_exp_f32_e32 v57, v57
	s_waitcnt lgkmcnt(9)
	v_mfma_f32_32x32x16_bf16 v[96:111], v[128:131], v[164:167], v[0:15]
	ds_read_b128 v[226:229], v187 offset:51712
	v_exp_f32_e32 v58, v58
	v_exp_f32_e32 v59, v59
	v_add_f32_e32 v48, v64, v48
	v_add_f32_e32 v244, v244, v48
	s_waitcnt lgkmcnt(9)
	v_mfma_f32_32x32x16_bf16 v[96:111], v[132:135], v[144:147], v[96:111]
	ds_read_b128 v[128:131], v187 offset:51744
	v_exp_f32_e32 v60, v60
	v_exp_f32_e32 v61, v61
	v_add_f32_e32 v49, v65, v49
	v_add_f32_e32 v245, v245, v49
	s_waitcnt lgkmcnt(9)
	v_mfma_f32_32x32x16_bf16 v[96:111], v[136:139], v[148:151], v[96:111]
	ds_read_b128 v[132:135], v187 offset:51776
	v_exp_f32_e32 v62, v62
	v_exp_f32_e32 v63, v63
	v_add_f32_e32 v50, v66, v50
	v_add_f32_e32 v242, v242, v50
	s_waitcnt lgkmcnt(9)
	v_mfma_f32_32x32x16_bf16 v[96:111], v[140:143], v[152:155], v[96:111]
	ds_read_b128 v[136:139], v209 offset:35936
	v_cvt_pk_bf16_f32 v124, v56, v57
	v_cvt_pk_bf16_f32 v125, v58, v59
	v_cvt_pk_bf16_f32 v126, v60, v61
	v_cvt_pk_bf16_f32 v127, v62, v63
	v_add_f32_e32 v51, v67, v51
	v_add_f32_e32 v243, v243, v51
	s_waitcnt lgkmcnt(9)
	v_mfma_f32_32x32x16_bf16 v[96:111], v[188:191], v[156:159], v[96:111]
	ds_read_b128 v[140:143], v209 offset:40544
	v_add_f32_e32 v52, v68, v52
	v_add_f32_e32 v240, v240, v52
	v_add_f32_e32 v53, v69, v53
	v_add_f32_e32 v241, v241, v53
	v_add_f32_e32 v54, v70, v54
	v_add_f32_e32 v238, v238, v54
	s_waitcnt lgkmcnt(7)
	v_mfma_f32_32x32x16_bf16 v[96:111], v[168:171], v[160:163], v[96:111]
	ds_read_b128 v[188:191], v187 offset:51808
	v_add_f32_e32 v55, v71, v55
	v_add_f32_e32 v239, v239, v55
	v_add_f32_e32 v56, v72, v56
	v_add_f32_e32 v236, v236, v56
	v_add_f32_e32 v57, v73, v57
	v_add_f32_e32 v237, v237, v57
	s_waitcnt lgkmcnt(7)
	v_mfma_f32_32x32x16_bf16 v[16:31], v[218:221], v[120:123], v[16:31]
	ds_read_b128 v[168:171], v187 offset:51840
	v_add_f32_e32 v58, v74, v58
	v_add_f32_e32 v234, v234, v58
	v_add_f32_e32 v59, v75, v59
	v_add_f32_e32 v235, v235, v59
	v_add_f32_e32 v60, v76, v60
	v_add_f32_e32 v232, v232, v60
	s_waitcnt lgkmcnt(7)
	v_mfma_f32_32x32x16_bf16 v[32:47], v[222:225], v[120:123], v[32:47]
	ds_read_b128 v[218:221], v187 offset:51872
	v_add_f32_e32 v61, v77, v61
	v_add_f32_e32 v233, v233, v61
	v_add_f32_e32 v62, v78, v62
	v_add_f32_e32 v230, v230, v62
	s_waitcnt lgkmcnt(7)
	v_mfma_f32_32x32x16_bf16 v[80:95], v[226:229], v[164:167], v[0:15]
	ds_read_b128 v[222:225], v209 offset:58368
	v_exp_f32_e32 v96, v96
	v_exp_f32_e32 v97, v97
	v_exp_f32_e32 v98, v98
	s_waitcnt lgkmcnt(7)
	v_mfma_f32_32x32x16_bf16 v[80:95], v[128:131], v[144:147], v[80:95]
	ds_read_b128 v[226:229], v209 offset:62976
	v_exp_f32_e32 v99, v99
	v_exp_f32_e32 v100, v100
	v_exp_f32_e32 v101, v101
	s_waitcnt lgkmcnt(7)
	v_mfma_f32_32x32x16_bf16 v[80:95], v[132:135], v[148:151], v[80:95]
	ds_read_b128 v[128:131], v209 offset:58400
	v_exp_f32_e32 v102, v102
	v_exp_f32_e32 v103, v103
	v_cvt_pk_bf16_f32 v112, v96, v97
	v_cvt_pk_bf16_f32 v113, v98, v99
	s_waitcnt lgkmcnt(7)
	v_mfma_f32_32x32x16_bf16 v[16:31], v[136:139], v[124:127], v[16:31]
	ds_read_b128 v[132:135], v209 offset:63008
	v_cvt_pk_bf16_f32 v114, v100, v101
	v_cvt_pk_bf16_f32 v115, v102, v103
	v_exp_f32_e32 v104, v104
	v_exp_f32_e32 v105, v105
	s_waitcnt lgkmcnt(7)
	v_mfma_f32_32x32x16_bf16 v[32:47], v[140:143], v[124:127], v[32:47]
	v_exp_f32_e32 v106, v106
	v_exp_f32_e32 v107, v107
	v_exp_f32_e32 v108, v108
	s_waitcnt lgkmcnt(6)
	v_mfma_f32_32x32x16_bf16 v[80:95], v[188:191], v[152:155], v[80:95]
	v_exp_f32_e32 v109, v109
	v_exp_f32_e32 v110, v110
	v_exp_f32_e32 v111, v111
	s_waitcnt lgkmcnt(5)
	v_mfma_f32_32x32x16_bf16 v[80:95], v[168:171], v[156:159], v[80:95]
	v_cvt_pk_bf16_f32 v116, v104, v105
	v_cvt_pk_bf16_f32 v117, v106, v107
	v_cvt_pk_bf16_f32 v118, v108, v109
	v_cvt_pk_bf16_f32 v119, v110, v111
	s_waitcnt lgkmcnt(4)
	v_mfma_f32_32x32x16_bf16 v[80:95], v[218:221], v[160:163], v[80:95]
	v_add_f32_e32 v63, v79, v63
	v_add_f32_e32 v231, v231, v63
	s_waitcnt lgkmcnt(4)
	s_barrier
	ds_read_b128 v[136:139], v187 offset:0
	ds_read_b128 v[140:143], v187 offset:32
	ds_read_b128 v[188:191], v187 offset:64
	ds_read_b128 v[168:171], v187 offset:96
	s_waitcnt lgkmcnt(7)
	v_mfma_f32_32x32x16_bf16 v[16:31], v[222:225], v[112:115], v[16:31]
	ds_read_b128 v[218:221], v187 offset:128
	s_waitcnt vmcnt(0)
	ds_write_b128 v211, v[176:179] offset:22528
	s_and_saveexec_b64 s[42:43], s[36:37]
	s_cbranch_execz .Lattn_fx_w34
	ds_write_b128 v186, v[172:175] offset:22528
.Lattn_fx_w34:
	s_or_b64 exec, exec, s[42:43]
	ds_write_b128 v208, v[180:183] offset:35840
	v_exp_f32_e32 v80, v80
	v_exp_f32_e32 v81, v81
	v_exp_f32_e32 v82, v82
	s_waitcnt lgkmcnt(9)
	v_mfma_f32_32x32x16_bf16 v[32:47], v[226:229], v[112:115], v[32:47]
	ds_read_b128 v[222:225], v187 offset:160
	s_cmp_eq_u32 s14, 6
	s_cbranch_scc1 .Lattn_fx_skipld
	global_load_dwordx4 v[176:179], v212, s[6:7]
	s_and_saveexec_b64 s[42:43], s[36:37]
	s_cbranch_execz .Lattn_fx_g35
	global_load_dwordx4 v[172:175], v214, s[6:7]

.Lattn_fx_skipld:
	v_exp_f32_e32 v83, v83
	v_exp_f32_e32 v84, v84
	v_exp_f32_e32 v85, v85
	s_waitcnt lgkmcnt(9)
	v_mfma_f32_32x32x16_bf16 v[16:31], v[128:131], v[116:119], v[16:31]
	ds_read_b128 v[226:229], v209 offset:58432
	v_exp_f32_e32 v86, v86
	v_exp_f32_e32 v87, v87
	v_cvt_pk_bf16_f32 v120, v80, v81
	v_cvt_pk_bf16_f32 v121, v82, v83
	s_waitcnt lgkmcnt(9)
	v_mfma_f32_32x32x16_bf16 v[32:47], v[132:135], v[116:119], v[32:47]
	ds_read_b128 v[128:131], v209 offset:63040
	v_cvt_pk_bf16_f32 v122, v84, v85
	v_cvt_pk_bf16_f32 v123, v86, v87
	v_exp_f32_e32 v88, v88
	v_exp_f32_e32 v89, v89
	s_waitcnt lgkmcnt(9)
	v_mfma_f32_32x32x16_bf16 v[64:79], v[136:139], v[164:167], v[0:15]
	ds_read_b128 v[132:135], v187 offset:6656
	v_exp_f32_e32 v90, v90
	v_exp_f32_e32 v91, v91
	v_add_f32_e32 v80, v96, v80
	v_add_f32_e32 v244, v244, v80
	s_waitcnt lgkmcnt(9)
	v_mfma_f32_32x32x16_bf16 v[64:79], v[140:143], v[144:147], v[64:79]
	ds_read_b128 v[136:139], v187 offset:6688
	v_exp_f32_e32 v92, v92
	v_exp_f32_e32 v93, v93
	v_add_f32_e32 v81, v97, v81
	v_add_f32_e32 v245, v245, v81
	s_waitcnt lgkmcnt(9)
	v_mfma_f32_32x32x16_bf16 v[64:79], v[188:191], v[148:151], v[64:79]
	ds_read_b128 v[140:143], v187 offset:6720
	v_exp_f32_e32 v94, v94
	v_exp_f32_e32 v95, v95
	v_add_f32_e32 v82, v98, v82
	v_add_f32_e32 v242, v242, v82
	s_waitcnt lgkmcnt(9)
	v_mfma_f32_32x32x16_bf16 v[64:79], v[168:171], v[152:155], v[64:79]
	ds_read_b128 v[188:191], v209 offset:58464
	v_cvt_pk_bf16_f32 v124, v88, v89
	v_cvt_pk_bf16_f32 v125, v90, v91
	v_cvt_pk_bf16_f32 v126, v92, v93
	v_cvt_pk_bf16_f32 v127, v94, v95
	v_add_f32_e32 v83, v99, v83
	v_add_f32_e32 v243, v243, v83
	s_waitcnt lgkmcnt(9)
	v_mfma_f32_32x32x16_bf16 v[64:79], v[218:221], v[156:159], v[64:79]
	ds_read_b128 v[168:171], v209 offset:63072
	v_add_f32_e32 v84, v100, v84
	v_add_f32_e32 v240, v240, v84
	v_add_f32_e32 v85, v101, v85
	v_add_f32_e32 v241, v241, v85
	v_add_f32_e32 v86, v102, v86
	v_add_f32_e32 v238, v238, v86
	s_waitcnt lgkmcnt(7)
	v_mfma_f32_32x32x16_bf16 v[64:79], v[222:225], v[160:163], v[64:79]
	ds_read_b128 v[218:221], v187 offset:6752
	v_add_f32_e32 v87, v103, v87
	v_add_f32_e32 v239, v239, v87
	v_add_f32_e32 v88, v104, v88
	v_add_f32_e32 v236, v236, v88
	v_add_f32_e32 v89, v105, v89
	v_add_f32_e32 v237, v237, v89
	s_waitcnt lgkmcnt(7)
	v_mfma_f32_32x32x16_bf16 v[16:31], v[226:229], v[120:123], v[16:31]
	ds_read_b128 v[222:225], v187 offset:6784
	v_add_f32_e32 v90, v106, v90
	v_add_f32_e32 v234, v234, v90
	v_add_f32_e32 v91, v107, v91
	v_add_f32_e32 v235, v235, v91
	v_add_f32_e32 v92, v108, v92
	v_add_f32_e32 v232, v232, v92
	s_waitcnt lgkmcnt(7)
	v_mfma_f32_32x32x16_bf16 v[32:47], v[128:131], v[120:123], v[32:47]
	ds_read_b128 v[226:229], v187 offset:6816
	v_add_f32_e32 v93, v109, v93
	v_add_f32_e32 v233, v233, v93
	v_add_f32_e32 v94, v110, v94
	v_add_f32_e32 v230, v230, v94
	s_waitcnt lgkmcnt(7)
	v_mfma_f32_32x32x16_bf16 v[48:63], v[132:135], v[164:167], v[0:15]
	ds_read_b128 v[128:131], v209 offset:13312
	v_exp_f32_e32 v64, v64
	v_exp_f32_e32 v65, v65
	v_exp_f32_e32 v66, v66
	s_waitcnt lgkmcnt(7)
	v_mfma_f32_32x32x16_bf16 v[48:63], v[136:139], v[144:147], v[48:63]
	ds_read_b128 v[132:135], v209 offset:17920
	v_exp_f32_e32 v67, v67
	v_exp_f32_e32 v68, v68
	v_exp_f32_e32 v69, v69
	s_waitcnt lgkmcnt(7)
	v_mfma_f32_32x32x16_bf16 v[48:63], v[140:143], v[148:151], v[48:63]
	ds_read_b128 v[136:139], v209 offset:13344
	v_exp_f32_e32 v70, v70
	v_exp_f32_e32 v71, v71
	v_cvt_pk_bf16_f32 v112, v64, v65
	v_cvt_pk_bf16_f32 v113, v66, v67
	s_waitcnt lgkmcnt(7)
	v_mfma_f32_32x32x16_bf16 v[16:31], v[188:191], v[124:127], v[16:31]
	ds_read_b128 v[140:143], v209 offset:17952
	v_cvt_pk_bf16_f32 v114, v68, v69
	v_cvt_pk_bf16_f32 v115, v70, v71
	v_exp_f32_e32 v72, v72
	v_exp_f32_e32 v73, v73
	s_waitcnt lgkmcnt(7)
	v_mfma_f32_32x32x16_bf16 v[32:47], v[168:171], v[124:127], v[32:47]
	v_exp_f32_e32 v74, v74
	v_exp_f32_e32 v75, v75
	v_exp_f32_e32 v76, v76
	s_waitcnt lgkmcnt(6)
	v_mfma_f32_32x32x16_bf16 v[48:63], v[218:221], v[152:155], v[48:63]
	v_exp_f32_e32 v77, v77
	v_exp_f32_e32 v78, v78
	v_exp_f32_e32 v79, v79
	s_waitcnt lgkmcnt(5)
	v_mfma_f32_32x32x16_bf16 v[48:63], v[222:225], v[156:159], v[48:63]
	v_cvt_pk_bf16_f32 v116, v72, v73
	v_cvt_pk_bf16_f32 v117, v74, v75
	v_cvt_pk_bf16_f32 v118, v76, v77
	v_cvt_pk_bf16_f32 v119, v78, v79
	s_waitcnt lgkmcnt(4)
	v_mfma_f32_32x32x16_bf16 v[48:63], v[226:229], v[160:163], v[48:63]
	v_add_f32_e32 v95, v111, v95
	v_add_f32_e32 v231, v231, v95
	s_waitcnt lgkmcnt(4)
	s_barrier
	s_add_i32 s14, s14, 1
	s_cmp_lt_u32 s14, 7
	s_cbranch_scc1 .Lattn_fx_loop
	ds_read_b128 v[188:191], v187 offset:22528
	ds_read_b128 v[168:171], v187 offset:22560
	ds_read_b128 v[218:221], v187 offset:22592
	ds_read_b128 v[222:225], v187 offset:22624
	s_waitcnt lgkmcnt(7)
	v_mfma_f32_32x32x16_bf16 v[16:31], v[128:131], v[112:115], v[16:31]
	ds_read_b128 v[226:229], v187 offset:22656
	s_nop 7
	v_exp_f32_e32 v48, v48
	v_exp_f32_e32 v49, v49
	v_exp_f32_e32 v50, v50
	s_waitcnt lgkmcnt(7)
	v_mfma_f32_32x32x16_bf16 v[32:47], v[132:135], v[112:115], v[32:47]
	ds_read_b128 v[128:131], v187 offset:22688
	v_exp_f32_e32 v51, v51
	v_exp_f32_e32 v52, v52
	v_exp_f32_e32 v53, v53
	s_waitcnt lgkmcnt(7)
	v_mfma_f32_32x32x16_bf16 v[16:31], v[136:139], v[116:119], v[16:31]
	ds_read_b128 v[132:135], v209 offset:13376
	v_exp_f32_e32 v54, v54
	v_exp_f32_e32 v55, v55
	v_cvt_pk_bf16_f32 v120, v48, v49
	v_cvt_pk_bf16_f32 v121, v50, v51
	s_waitcnt lgkmcnt(7)
	v_mfma_f32_32x32x16_bf16 v[32:47], v[140:143], v[116:119], v[32:47]
	ds_read_b128 v[136:139], v209 offset:17984
	v_cvt_pk_bf16_f32 v122, v52, v53
	v_cvt_pk_bf16_f32 v123, v54, v55
	v_exp_f32_e32 v56, v56
	v_exp_f32_e32 v57, v57
	s_waitcnt lgkmcnt(7)
	v_mfma_f32_32x32x16_bf16 v[96:111], v[188:191], v[164:167], v[0:15]
	ds_read_b128 v[140:143], v187 offset:29184
	v_exp_f32_e32 v58, v58
	v_exp_f32_e32 v59, v59
	v_add_f32_e32 v48, v64, v48
	v_add_f32_e32 v244, v244, v48
	s_waitcnt lgkmcnt(7)
	v_mfma_f32_32x32x16_bf16 v[96:111], v[168:171], v[144:147], v[96:111]
	ds_read_b128 v[188:191], v187 offset:29216
	v_exp_f32_e32 v60, v60
	v_exp_f32_e32 v61, v61
	v_add_f32_e32 v49, v65, v49
	v_add_f32_e32 v245, v245, v49
	s_waitcnt lgkmcnt(7)
	v_mfma_f32_32x32x16_bf16 v[96:111], v[218:221], v[148:151], v[96:111]
	ds_read_b128 v[168:171], v187 offset:29248
	v_exp_f32_e32 v62, v62
	v_exp_f32_e32 v63, v63
	v_add_f32_e32 v50, v66, v50
	v_add_f32_e32 v242, v242, v50
	s_waitcnt lgkmcnt(7)
	v_mfma_f32_32x32x16_bf16 v[96:111], v[222:225], v[152:155], v[96:111]
	ds_read_b128 v[218:221], v209 offset:13408
	v_cvt_pk_bf16_f32 v124, v56, v57
	v_cvt_pk_bf16_f32 v125, v58, v59
	v_cvt_pk_bf16_f32 v126, v60, v61
	v_cvt_pk_bf16_f32 v127, v62, v63
	v_add_f32_e32 v51, v67, v51
	v_add_f32_e32 v243, v243, v51
	s_waitcnt lgkmcnt(7)
	v_mfma_f32_32x32x16_bf16 v[96:111], v[226:229], v[156:159], v[96:111]
	ds_read_b128 v[222:225], v209 offset:18016
	v_add_f32_e32 v52, v68, v52
	v_add_f32_e32 v240, v240, v52
	v_add_f32_e32 v53, v69, v53
	v_add_f32_e32 v241, v241, v53
	v_add_f32_e32 v54, v70, v54
	v_add_f32_e32 v238, v238, v54
	s_waitcnt lgkmcnt(7)
	v_mfma_f32_32x32x16_bf16 v[96:111], v[128:131], v[160:163], v[96:111]
	ds_read_b128 v[226:229], v187 offset:29280
	v_add_f32_e32 v55, v71, v55
	v_add_f32_e32 v239, v239, v55
	v_add_f32_e32 v56, v72, v56
	v_add_f32_e32 v236, v236, v56
	v_add_f32_e32 v57, v73, v57
	v_add_f32_e32 v237, v237, v57
	s_waitcnt lgkmcnt(7)
	v_mfma_f32_32x32x16_bf16 v[16:31], v[132:135], v[120:123], v[16:31]
	ds_read_b128 v[128:131], v187 offset:29312
	v_add_f32_e32 v58, v74, v58
	v_add_f32_e32 v234, v234, v58
	v_add_f32_e32 v59, v75, v59
	v_add_f32_e32 v235, v235, v59
	v_add_f32_e32 v60, v76, v60
	v_add_f32_e32 v232, v232, v60
	s_waitcnt lgkmcnt(7)
	v_mfma_f32_32x32x16_bf16 v[32:47], v[136:139], v[120:123], v[32:47]
	ds_read_b128 v[132:135], v187 offset:29344
	v_add_f32_e32 v61, v77, v61
	v_add_f32_e32 v233, v233, v61
	v_add_f32_e32 v62, v78, v62
	v_add_f32_e32 v230, v230, v62
	s_waitcnt lgkmcnt(7)
	v_mfma_f32_32x32x16_bf16 v[80:95], v[140:143], v[164:167], v[0:15]
	ds_read_b128 v[136:139], v209 offset:35840
	v_exp_f32_e32 v96, v96
	v_exp_f32_e32 v97, v97
	v_exp_f32_e32 v98, v98
	s_waitcnt lgkmcnt(7)
	v_mfma_f32_32x32x16_bf16 v[80:95], v[188:191], v[144:147], v[80:95]
	ds_read_b128 v[140:143], v209 offset:40448
	v_exp_f32_e32 v99, v99
	v_exp_f32_e32 v100, v100
	v_exp_f32_e32 v101, v101
	s_waitcnt lgkmcnt(7)
	v_mfma_f32_32x32x16_bf16 v[80:95], v[168:171], v[148:151], v[80:95]
	ds_read_b128 v[188:191], v209 offset:35872
	v_exp_f32_e32 v102, v102
	v_exp_f32_e32 v103, v103
	v_cvt_pk_bf16_f32 v112, v96, v97
	v_cvt_pk_bf16_f32 v113, v98, v99
	s_waitcnt lgkmcnt(7)
	v_mfma_f32_32x32x16_bf16 v[16:31], v[218:221], v[124:127], v[16:31]
	ds_read_b128 v[168:171], v209 offset:40480
	v_cvt_pk_bf16_f32 v114, v100, v101
	v_cvt_pk_bf16_f32 v115, v102, v103
	v_exp_f32_e32 v104, v104
	v_exp_f32_e32 v105, v105
	s_waitcnt lgkmcnt(7)
	v_mfma_f32_32x32x16_bf16 v[32:47], v[222:225], v[124:127], v[32:47]
	v_exp_f32_e32 v106, v106
	v_exp_f32_e32 v107, v107
	v_exp_f32_e32 v108, v108
	s_waitcnt lgkmcnt(6)
	v_mfma_f32_32x32x16_bf16 v[80:95], v[226:229], v[152:155], v[80:95]
	v_exp_f32_e32 v109, v109
	v_exp_f32_e32 v110, v110
	v_exp_f32_e32 v111, v111
	s_waitcnt lgkmcnt(5)
	v_mfma_f32_32x32x16_bf16 v[80:95], v[128:131], v[156:159], v[80:95]
	v_cvt_pk_bf16_f32 v116, v104, v105
	v_cvt_pk_bf16_f32 v117, v106, v107
	v_cvt_pk_bf16_f32 v118, v108, v109
	v_cvt_pk_bf16_f32 v119, v110, v111
	s_waitcnt lgkmcnt(4)
	v_mfma_f32_32x32x16_bf16 v[80:95], v[132:135], v[160:163], v[80:95]
	v_add_f32_e32 v63, v79, v63
	v_add_f32_e32 v231, v231, v63
	s_waitcnt lgkmcnt(4)
	s_barrier
	ds_read_b128 v[218:221], v209 offset:35904
	ds_read_b128 v[222:225], v209 offset:40512
	ds_read_b128 v[226:229], v209 offset:35936
	ds_read_b128 v[128:131], v209 offset:40544
	s_waitcnt lgkmcnt(7)
	v_mfma_f32_32x32x16_bf16 v[16:31], v[136:139], v[112:115], v[16:31]
	s_nop 7
	v_exp_f32_e32 v80, v80
	v_exp_f32_e32 v81, v81
	v_exp_f32_e32 v82, v82
	v_exp_f32_e32 v83, v83
	v_exp_f32_e32 v84, v84
	v_exp_f32_e32 v85, v85
	v_exp_f32_e32 v86, v86
	v_exp_f32_e32 v87, v87
	s_waitcnt lgkmcnt(6)
	v_mfma_f32_32x32x16_bf16 v[32:47], v[140:143], v[112:115], v[32:47]
	v_cvt_pk_bf16_f32 v120, v80, v81
	v_cvt_pk_bf16_f32 v121, v82, v83
	v_cvt_pk_bf16_f32 v122, v84, v85
	v_cvt_pk_bf16_f32 v123, v86, v87
	v_exp_f32_e32 v88, v88
	v_exp_f32_e32 v89, v89
	v_exp_f32_e32 v90, v90
	v_exp_f32_e32 v91, v91
	s_waitcnt lgkmcnt(5)
	v_mfma_f32_32x32x16_bf16 v[16:31], v[188:191], v[116:119], v[16:31]
	v_exp_f32_e32 v92, v92
	v_exp_f32_e32 v93, v93
	v_exp_f32_e32 v94, v94
	v_exp_f32_e32 v95, v95
	s_waitcnt lgkmcnt(4)
	v_mfma_f32_32x32x16_bf16 v[32:47], v[168:171], v[116:119], v[32:47]
	v_cvt_pk_bf16_f32 v124, v88, v89
	v_cvt_pk_bf16_f32 v125, v90, v91
	v_cvt_pk_bf16_f32 v126, v92, v93
	v_cvt_pk_bf16_f32 v127, v94, v95
	s_waitcnt lgkmcnt(3)
	v_mfma_f32_32x32x16_bf16 v[16:31], v[218:221], v[120:123], v[16:31]
	v_add_f32_e32 v80, v96, v80
	v_add_f32_e32 v244, v244, v80
	v_add_f32_e32 v81, v97, v81
	v_add_f32_e32 v245, v245, v81
	v_add_f32_e32 v82, v98, v82
	v_add_f32_e32 v242, v242, v82
	v_add_f32_e32 v83, v99, v83
	v_add_f32_e32 v243, v243, v83
	s_waitcnt lgkmcnt(2)
	v_mfma_f32_32x32x16_bf16 v[32:47], v[222:225], v[120:123], v[32:47]
	v_add_f32_e32 v84, v100, v84
	v_add_f32_e32 v240, v240, v84
	v_add_f32_e32 v85, v101, v85
	v_add_f32_e32 v241, v241, v85
	v_add_f32_e32 v86, v102, v86
	v_add_f32_e32 v238, v238, v86
	v_add_f32_e32 v87, v103, v87
	v_add_f32_e32 v239, v239, v87
	s_waitcnt lgkmcnt(1)
	v_mfma_f32_32x32x16_bf16 v[16:31], v[226:229], v[124:127], v[16:31]
	v_add_f32_e32 v88, v104, v88
	v_add_f32_e32 v236, v236, v88
	v_add_f32_e32 v89, v105, v89
	v_add_f32_e32 v237, v237, v89
	v_add_f32_e32 v90, v106, v90
	v_add_f32_e32 v234, v234, v90
	v_add_f32_e32 v91, v107, v91
	v_add_f32_e32 v235, v235, v91
	s_waitcnt lgkmcnt(0)
	v_mfma_f32_32x32x16_bf16 v[32:47], v[128:131], v[124:127], v[32:47]
	v_add_f32_e32 v92, v108, v92
	v_add_f32_e32 v232, v232, v92
	v_add_f32_e32 v93, v109, v93
	v_add_f32_e32 v233, v233, v93
	v_add_f32_e32 v94, v110, v94
	v_add_f32_e32 v230, v230, v94
	v_add_f32_e32 v95, v111, v95
	v_add_f32_e32 v231, v231, v95
	s_waitcnt lgkmcnt(0)
	s_barrier
